# router: token registers re-paired (16 v_swap per 4-token group) so packed FMAs take broadcast weights via op_sel (no weight movs) and per-token sums accumulate with packed adds; same per-token operati
# speedup vs baseline: 1.0386x; 1.0039x over previous
; DEVI void ln_inplace(float4 (&v)[4], const float* __restrict__ g, const float* __restrict__ b, int lane) {
;   float s = 0.f;
; #pragma unroll
;   for (int j = 0; j < 4; ++j) s += v[j].x + v[j].y + v[j].z + v[j].w;
;   s = wave_sum(s);
;   const float mu = s * (1.f / 1024.f);
;   float q = 0.f;
; #pragma unroll
;   for (int j = 0; j < 4; ++j) {
;     float a = v[j].x - mu, bq = v[j].y - mu, cq = v[j].z - mu, d = v[j].w - mu;
;     q += a * a + bq * bq + cq * cq + d * d;
;   }
;   q = wave_sum(q);
;   const float rs = rsqrtf(q * (1.f / 1024.f) + EPS);
; DEVI void phase_p7(const int TIDX, const int BIDX, const int GDIM, KAP KA, unsigned char* WSB, float* OUTB, int l, unsigned char* smem) {
;     ...
;       for (int t = 0; t < 4; ++t) {
;         const size_t row = (size_t)r4 * 4 + t;
; #pragma unroll
;         for (int j = 0; j < 4; ++j) v[t][j] = resid_plus(*(const uint2*)(XB + row * 1024 + j * 256 + lane * 4), *(const uint2*)((const bf16_t*)PRE + row * 1024 + j * 256 + lane * 4));
;         ln_inplace(v[t], g1, b1, lane);
.LBB0_68:
	v_ashrrev_i32_e32 v33, 31, v32
	v_lshlrev_b64 v[70:71], 13, v[32:33]
	v_lshl_add_u64 v[54:55], v[34:35], 0, v[70:71]
	global_load_dwordx2 v[46:47], v[54:55], off offset:1024
	global_load_dwordx2 v[50:51], v[54:55], off offset:1536
	v_lshl_add_u64 v[0:1], v[36:37], 0, v[70:71]
	global_load_dwordx2 v[52:53], v[0:1], off offset:1536
	global_load_dwordx2 v[48:49], v[0:1], off offset:1024
	global_load_dwordx2 v[56:57], v[54:55], off offset:512
	global_load_dwordx2 v[58:59], v[54:55], off
	global_load_dwordx2 v[60:61], v[0:1], off offset:512
	global_load_dwordx2 v[62:63], v[0:1], off
	global_load_dwordx4 v[24:27], v[38:39], off
	s_nop 0
	global_load_dwordx4 v[0:3], v[38:39], off offset:1024
	global_load_dwordx4 v[28:31], v[40:41], off
	global_load_dwordx4 v[4:7], v[40:41], off offset:1024
	global_load_dwordx4 v[16:19], v[38:39], off offset:2048
	global_load_dwordx4 v[8:11], v[38:39], off offset:3072
	global_load_dwordx4 v[20:23], v[40:41], off offset:2048
	global_load_dwordx4 v[12:15], v[40:41], off offset:3072
	v_or_b32_e32 v64, 0x800, v70
	v_mov_b32_e32 v65, v71
	v_lshl_add_u64 v[76:77], v[34:35], 0, v[64:65]
	v_lshl_add_u64 v[64:65], v[36:37], 0, v[64:65]
	global_load_dwordx2 v[66:67], v[76:77], off offset:1024
	global_load_dwordx2 v[68:69], v[76:77], off offset:1536
	global_load_dwordx2 v[72:73], v[76:77], off
	global_load_dwordx2 v[74:75], v[76:77], off offset:512
	global_load_dwordx2 v[78:79], v[64:65], off offset:1024
	global_load_dwordx2 v[80:81], v[64:65], off offset:1536
	global_load_dwordx2 v[82:83], v[64:65], off
	s_nop 0
	global_load_dwordx2 v[64:65], v[64:65], off offset:512
	s_mov_b32 s22, 0x3a800000
	s_waitcnt vmcnt(21)
	v_lshlrev_b32_e32 v93, 16, v52
	s_waitcnt vmcnt(20)
	v_lshlrev_b32_e32 v92, 16, v48
	v_and_b32_e32 v97, 0xffff0000, v52
	v_and_b32_e32 v96, 0xffff0000, v48
	v_lshlrev_b32_e32 v101, 16, v53
	v_lshlrev_b32_e32 v100, 16, v49
	s_waitcnt vmcnt(18)
	v_lshlrev_b32_e32 v48, 16, v58
	s_waitcnt vmcnt(16)
	v_lshlrev_b32_e32 v52, 16, v62
	v_and_b32_e32 v103, 0xffff0000, v56
	v_and_b32_e32 v102, 0xffff0000, v58
	v_lshlrev_b32_e32 v90, 16, v46
	v_lshlrev_b32_e32 v91, 16, v50
	v_and_b32_e32 v95, 0xffff0000, v50
	v_and_b32_e32 v94, 0xffff0000, v46
	v_lshlrev_b32_e32 v99, 16, v51
	v_lshlrev_b32_e32 v98, 16, v47
	v_and_b32_e32 v51, 0xffff0000, v51
	v_and_b32_e32 v50, 0xffff0000, v47
	v_and_b32_e32 v47, 0xffff0000, v53
	v_and_b32_e32 v46, 0xffff0000, v49
	v_lshlrev_b32_e32 v49, 16, v56
	v_lshlrev_b32_e32 v53, 16, v60
	v_and_b32_e32 v105, 0xffff0000, v60
	v_and_b32_e32 v104, 0xffff0000, v62
	v_lshlrev_b32_e32 v107, 16, v57
	v_lshlrev_b32_e32 v106, 16, v59
	v_lshlrev_b32_e32 v109, 16, v61
	v_lshlrev_b32_e32 v108, 16, v63
	v_pk_fma_f32 v[46:47], v[50:51], s[64:65], v[46:47] op_sel_hi:[1,0,1]
	v_pk_fma_f32 v[48:49], v[48:49], s[64:65], v[52:53] op_sel_hi:[1,0,1]
	v_pk_fma_f32 v[50:51], v[102:103], s[64:65], v[104:105] op_sel_hi:[1,0,1]
	v_and_b32_e32 v57, 0xffff0000, v57
	v_and_b32_e32 v56, 0xffff0000, v59
	v_and_b32_e32 v59, 0xffff0000, v61
	v_and_b32_e32 v58, 0xffff0000, v63
	v_pk_fma_f32 v[60:61], v[90:91], s[64:65], v[92:93] op_sel_hi:[1,0,1]
	v_pk_fma_f32 v[52:53], v[106:107], s[64:65], v[108:109] op_sel_hi:[1,0,1]
	v_pk_add_f32 v[92:93], v[48:49], v[50:51]
	v_pk_fma_f32 v[62:63], v[94:95], s[64:65], v[96:97] op_sel_hi:[1,0,1]
	v_pk_fma_f32 v[56:57], v[56:57], s[64:65], v[58:59] op_sel_hi:[1,0,1]
	v_pk_add_f32 v[92:93], v[92:93], v[52:53]
	v_pk_fma_f32 v[90:91], v[98:99], s[64:65], v[100:101] op_sel_hi:[1,0,1]
	v_pk_add_f32 v[58:59], v[60:61], v[62:63]
	v_pk_add_f32 v[92:93], v[56:57], v[92:93]
	v_pk_add_f32 v[58:59], v[58:59], v[90:91]
	v_add_f32_e32 v33, 0, v92
	v_pk_add_f32 v[58:59], v[46:47], v[58:59]
	v_add_f32_e32 v33, v33, v93
	v_add_f32_e32 v33, v33, v58
	v_add_f32_e32 v33, v33, v59
	s_waitcnt vmcnt(11)
	v_mov_b32_e32 v106, v16
	s_waitcnt vmcnt(10)
	v_mov_b32_e32 v107, v8
	v_add_f32_dpp v33, v33, v33 quad_perm:[1,0,3,2] row_mask:0xf bank_mask:0xf bound_ctrl:1
	s_waitcnt vmcnt(9)
	v_mov_b32_e32 v108, v20
	s_waitcnt vmcnt(8)
	v_mov_b32_e32 v109, v12
	v_add_f32_dpp v33, v33, v33 quad_perm:[2,3,0,1] row_mask:0xf bank_mask:0xf bound_ctrl:1
	v_mov_b32_e32 v8, v17
	v_mov_b32_e32 v12, v21
	v_add_f32_dpp v33, v33, v33 row_half_mirror row_mask:0xf bank_mask:0xf bound_ctrl:1
	s_waitcnt vmcnt(6)
	v_lshlrev_b32_e32 v17, 16, v68
	v_lshlrev_b32_e32 v16, 16, v66
	v_add_f32_dpp v33, v33, v33 row_mirror row_mask:0xf bank_mask:0xf bound_ctrl:1
	s_waitcnt vmcnt(2)
	v_lshlrev_b32_e32 v21, 16, v80
	v_readlane_b32 s2, v33, 16
	v_readlane_b32 s3, v33, 48
	v_readlane_b32 s0, v33, 0
	v_readlane_b32 s1, v33, 32
	v_mov_b32_e32 v58, s2
	v_mov_b32_e32 v59, s3
	v_pk_add_f32 v[58:59], s[0:1], v[58:59]
	v_lshlrev_b32_e32 v20, 16, v78
	v_add_f32_e32 v33, v58, v59
	v_mul_f32_e32 v58, 0x3a800000, v33
	v_pk_add_f32 v[50:51], v[50:51], v[58:59] op_sel_hi:[1,0] neg_lo:[0,1] neg_hi:[0,1]
	v_pk_add_f32 v[48:49], v[48:49], v[58:59] op_sel_hi:[1,0] neg_lo:[0,1] neg_hi:[0,1]
	v_pk_add_f32 v[92:93], v[56:57], v[58:59] op_sel_hi:[1,0] neg_lo:[0,1] neg_hi:[0,1]
	v_pk_mul_f32 v[56:57], v[50:51], v[50:51]
	v_pk_add_f32 v[52:53], v[52:53], v[58:59] op_sel_hi:[1,0] neg_lo:[0,1] neg_hi:[0,1]
	v_pk_fma_f32 v[56:57], v[48:49], v[48:49], v[56:57]
	v_pk_add_f32 v[94:95], v[60:61], v[58:59] op_sel_hi:[1,0] neg_lo:[0,1] neg_hi:[0,1]
	v_pk_fma_f32 v[56:57], v[52:53], v[52:53], v[56:57]
	v_pk_add_f32 v[96:97], v[62:63], v[58:59] op_sel_hi:[1,0] neg_lo:[0,1] neg_hi:[0,1]
	v_pk_fma_f32 v[56:57], v[92:93], v[92:93], v[56:57]
	v_pk_add_f32 v[90:91], v[90:91], v[58:59] op_sel_hi:[1,0] neg_lo:[0,1] neg_hi:[0,1]
	v_pk_add_f32 v[98:99], v[46:47], v[58:59] op_sel_hi:[1,0] neg_lo:[0,1] neg_hi:[0,1]
	v_add_f32_e32 v33, v56, v57
	v_lshlrev_b32_e32 v57, 16, v74
	v_lshlrev_b32_e32 v56, 16, v72
	s_waitcnt vmcnt(0)
; DEVI float lo2f(uint32_t u) { return __uint_as_float(u << 16); }
; DEVI float hi2f(uint32_t u) { return __uint_as_float(u & 0xffff0000u); }
; DEVI void ln_inplace(float4 (&v)[4], const float* __restrict__ g, const float* __restrict__ b, int lane) {
;   float s = 0.f;
; #pragma unroll
;   for (int j = 0; j < 4; ++j) s += v[j].x + v[j].y + v[j].z + v[j].w;
;   s = wave_sum(s);
;   const float mu = s * (1.f / 1024.f);
;   float q = 0.f;
; #pragma unroll
;   for (int j = 0; j < 4; ++j) {
;     float a = v[j].x - mu, bq = v[j].y - mu, cq = v[j].z - mu, d = v[j].w - mu;
;     q += a * a + bq * bq + cq * cq + d * d;
;   }
;   q = wave_sum(q);
;   const float rs = rsqrtf(q * (1.f / 1024.f) + EPS);
; DEVI float4 resid_plus(const uint2 xb, const uint2 mb) {
;   return make_float4(lo2f(xb.x) * DN_ALPHA + lo2f(mb.x), hi2f(xb.x) * DN_ALPHA + hi2f(mb.x), lo2f(xb.y) * DN_ALPHA + lo2f(mb.y), hi2f(xb.y) * DN_ALPHA + hi2f(mb.y));
; }
	v_lshlrev_b32_e32 v59, 16, v64
	v_lshlrev_b32_e32 v58, 16, v82
	v_pk_fma_f32 v[56:57], v[56:57], s[64:65], v[58:59] op_sel_hi:[1,0,1]
	v_and_b32_e32 v59, 0xffff0000, v74
	v_and_b32_e32 v58, 0xffff0000, v72
	v_and_b32_e32 v61, 0xffff0000, v64
	v_and_b32_e32 v60, 0xffff0000, v82
	v_pk_fma_f32 v[58:59], v[58:59], s[64:65], v[60:61] op_sel_hi:[1,0,1]
	v_lshlrev_b32_e32 v61, 16, v75
	v_lshlrev_b32_e32 v60, 16, v73
	v_lshlrev_b32_e32 v63, 16, v65
	v_lshlrev_b32_e32 v62, 16, v83
	v_mov_b32_e32 v100, v24
	v_mov_b32_e32 v101, v0
	v_mov_b32_e32 v0, v25
	v_pk_fma_f32 v[16:17], v[16:17], s[64:65], v[20:21] op_sel_hi:[1,0,1]
	v_and_b32_e32 v21, 0xffff0000, v68
	v_and_b32_e32 v20, 0xffff0000, v66
	v_and_b32_e32 v25, 0xffff0000, v80
	v_and_b32_e32 v24, 0xffff0000, v78
	v_pk_fma_f32 v[60:61], v[60:61], s[64:65], v[62:63] op_sel_hi:[1,0,1]
	v_and_b32_e32 v63, 0xffff0000, v75
	v_and_b32_e32 v62, 0xffff0000, v73
	v_and_b32_e32 v65, 0xffff0000, v65
	v_and_b32_e32 v64, 0xffff0000, v83
	v_pk_mul_f32 v[46:47], v[96:97], v[96:97]
	v_mov_b32_e32 v102, v28
	v_mov_b32_e32 v103, v4
	v_mov_b32_e32 v4, v29
	v_mov_b32_e32 v28, v26
	v_mov_b32_e32 v29, v2
	v_mov_b32_e32 v2, v27
	v_pk_fma_f32 v[20:21], v[20:21], s[64:65], v[24:25] op_sel_hi:[1,0,1]
	v_lshlrev_b32_e32 v25, 16, v69
	v_lshlrev_b32_e32 v24, 16, v67
	v_lshlrev_b32_e32 v27, 16, v81
	v_lshlrev_b32_e32 v26, 16, v79
	v_pk_fma_f32 v[62:63], v[62:63], s[64:65], v[64:65] op_sel_hi:[1,0,1]
	v_pk_add_f32 v[64:65], v[56:57], v[58:59]
	v_pk_fma_f32 v[46:47], v[94:95], v[94:95], v[46:47]
	v_mov_b32_e32 v104, v30
	v_mov_b32_e32 v105, v6
	v_mov_b32_e32 v6, v31
	v_pk_fma_f32 v[24:25], v[24:25], s[64:65], v[26:27] op_sel_hi:[1,0,1]
	v_and_b32_e32 v27, 0xffff0000, v69
	v_and_b32_e32 v26, 0xffff0000, v67
	v_and_b32_e32 v31, 0xffff0000, v81
	v_and_b32_e32 v30, 0xffff0000, v79
	v_pk_add_f32 v[64:65], v[64:65], v[60:61]
	v_pk_fma_f32 v[46:47], v[90:91], v[90:91], v[46:47]
	v_pk_fma_f32 v[26:27], v[26:27], s[64:65], v[30:31] op_sel_hi:[1,0,1]
	v_pk_add_f32 v[30:31], v[16:17], v[20:21]
	v_pk_add_f32 v[64:65], v[62:63], v[64:65]
	v_pk_fma_f32 v[46:47], v[98:99], v[98:99], v[46:47]
	v_mov_b32_e32 v111, v10
	v_pk_add_f32 v[30:31], v[30:31], v[24:25]
	v_add_f32_e32 v10, 0, v64
	v_add_f32_e32 v33, v46, v33
	v_pk_add_f32 v[30:31], v[26:27], v[30:31]
	v_add_f32_e32 v10, v10, v65
	v_add_f32_e32 v33, v47, v33
	v_add_f32_e32 v10, v10, v30
	v_add_f32_e32 v10, v10, v31
	v_add_f32_dpp v33, v33, v33 quad_perm:[1,0,3,2] row_mask:0xf bank_mask:0xf bound_ctrl:1
	v_mov_b32_e32 v110, v18
	v_add_f32_dpp v10, v10, v10 quad_perm:[1,0,3,2] row_mask:0xf bank_mask:0xf bound_ctrl:1
	v_add_f32_dpp v33, v33, v33 quad_perm:[2,3,0,1] row_mask:0xf bank_mask:0xf bound_ctrl:1
	v_mov_b32_e32 v112, v22
	v_add_f32_dpp v10, v10, v10 quad_perm:[2,3,0,1] row_mask:0xf bank_mask:0xf bound_ctrl:1
	v_add_f32_dpp v33, v33, v33 row_half_mirror row_mask:0xf bank_mask:0xf bound_ctrl:1
	v_mov_b32_e32 v113, v14
	v_add_f32_dpp v10, v10, v10 row_half_mirror row_mask:0xf bank_mask:0xf bound_ctrl:1
	v_add_f32_dpp v33, v33, v33 row_mirror row_mask:0xf bank_mask:0xf bound_ctrl:1
	v_mov_b32_e32 v14, v23
	v_readlane_b32 s2, v33, 16
	v_readlane_b32 s3, v33, 48
	v_add_f32_dpp v10, v10, v10 row_mirror row_mask:0xf bank_mask:0xf bound_ctrl:1
	v_readlane_b32 s0, v33, 0
	v_readlane_b32 s1, v33, 32
	v_mov_b32_e32 v46, s2
	v_mov_b32_e32 v47, s3
	v_readlane_b32 s2, v10, 16
	v_readlane_b32 s3, v10, 48
	v_pk_add_f32 v[46:47], s[0:1], v[46:47]
	v_readlane_b32 s0, v10, 0
	v_readlane_b32 s1, v10, 32
	v_mov_b32_e32 v30, s2
	v_mov_b32_e32 v31, s3
	v_pk_add_f32 v[30:31], s[0:1], v[30:31]
	s_nop 0
	v_add_f32_e32 v10, v30, v31
	v_mul_f32_e32 v10, 0x3a800000, v10
	v_pk_add_f32 v[66:67], v[56:57], v[10:11] op_sel_hi:[1,0] neg_lo:[0,1] neg_hi:[0,1]
	v_pk_add_f32 v[56:57], v[58:59], v[10:11] op_sel_hi:[1,0] neg_lo:[0,1] neg_hi:[0,1]
	v_pk_add_f32 v[64:65], v[20:21], v[10:11] op_sel_hi:[1,0] neg_lo:[0,1] neg_hi:[0,1]
	v_pk_mul_f32 v[30:31], v[56:57], v[56:57]
	v_pk_add_f32 v[58:59], v[60:61], v[10:11] op_sel_hi:[1,0] neg_lo:[0,1] neg_hi:[0,1]
	v_pk_add_f32 v[60:61], v[62:63], v[10:11] op_sel_hi:[1,0] neg_lo:[0,1] neg_hi:[0,1]
	v_pk_fma_f32 v[30:31], v[66:67], v[66:67], v[30:31]
	v_pk_add_f32 v[62:63], v[16:17], v[10:11] op_sel_hi:[1,0] neg_lo:[0,1] neg_hi:[0,1]
	v_pk_add_f32 v[20:21], v[24:25], v[10:11] op_sel_hi:[1,0] neg_lo:[0,1] neg_hi:[0,1]
	v_pk_mul_f32 v[24:25], v[64:65], v[64:65]
	v_pk_fma_f32 v[30:31], v[58:59], v[58:59], v[30:31]
	v_pk_fma_f32 v[24:25], v[62:63], v[62:63], v[24:25]
	v_pk_fma_f32 v[30:31], v[60:61], v[60:61], v[30:31]
	v_pk_add_f32 v[16:17], v[26:27], v[10:11] op_sel_hi:[1,0] neg_lo:[0,1] neg_hi:[0,1]
	v_pk_fma_f32 v[24:25], v[20:21], v[20:21], v[24:25]
	v_add_f32_e32 v10, v30, v31
	v_pk_fma_f32 v[24:25], v[16:17], v[16:17], v[24:25]
	v_mov_b32_e32 v27, v46
	v_add_f32_e32 v10, v24, v10
	v_add_f32_e32 v10, v25, v10
	s_nop 1
	v_add_f32_dpp v10, v10, v10 quad_perm:[1,0,3,2] row_mask:0xf bank_mask:0xf bound_ctrl:1
	s_nop 1
	v_add_f32_dpp v10, v10, v10 quad_perm:[2,3,0,1] row_mask:0xf bank_mask:0xf bound_ctrl:1
	s_nop 1
	v_add_f32_dpp v10, v10, v10 row_half_mirror row_mask:0xf bank_mask:0xf bound_ctrl:1
	s_nop 1
	v_add_f32_dpp v10, v10, v10 row_mirror row_mask:0xf bank_mask:0xf bound_ctrl:1
	s_nop 0
	v_readlane_b32 s2, v10, 16
	v_readlane_b32 s3, v10, 48
	v_readlane_b32 s0, v10, 0
	v_readlane_b32 s1, v10, 32
	v_mov_b32_e32 v24, s2
	v_mov_b32_e32 v25, s3
	v_pk_add_f32 v[24:25], s[0:1], v[24:25]
	s_mov_b32 s0, 0x358637bd
	v_mov_b32_e32 v26, v24
	v_mov_b32_e32 v46, v25
	v_pk_add_f32 v[24:25], v[26:27], v[46:47]
	v_mov_b64_e32 v[72:73], s[0:1]
	v_pk_fma_f32 v[68:69], v[24:25], s[22:23], v[72:73] op_sel_hi:[1,0,0]
; DEVI uint32_t pack2(float lo, float hi) { f32x2_t v = {lo, hi}; bf16x2_t b = __builtin_convertvector(v, bf16x2_t); return __builtin_bit_cast(uint32_t, b); }
; DEVI float lo2f(uint32_t u) { return __uint_as_float(u << 16); }
; DEVI float hi2f(uint32_t u) { return __uint_as_float(u & 0xffff0000u); }
; DEVI void ln_inplace(float4 (&v)[4], const float* __restrict__ g, const float* __restrict__ b, int lane) {
;   float s = 0.f;
; #pragma unroll
;   for (int j = 0; j < 4; ++j) s += v[j].x + v[j].y + v[j].z + v[j].w;
;   s = wave_sum(s);
;   const float mu = s * (1.f / 1024.f);
;   float q = 0.f;
; #pragma unroll
;   for (int j = 0; j < 4; ++j) {
;     float a = v[j].x - mu, bq = v[j].y - mu, cq = v[j].z - mu, d = v[j].w - mu;
;     q += a * a + bq * bq + cq * cq + d * d;
;   }
;   q = wave_sum(q);
;   const float rs = rsqrtf(q * (1.f / 1024.f) + EPS);
; #pragma unroll
;   for (int j = 0; j < 4; ++j) {
;     const float4 gg = *(const float4*)(g + j * 256 + lane * 4), bb = *(const float4*)(b + j * 256 + lane * 4);
;     v[j].x = (v[j].x - mu) * rs * gg.x + bb.x;
;     v[j].y = (v[j].y - mu) * rs * gg.y + bb.y;
;     v[j].z = (v[j].z - mu) * rs * gg.z + bb.z;
;     v[j].w = (v[j].w - mu) * rs * gg.w + bb.w;
;   }
; }
; DEVI void store_row(const float4 (&v)[4], float* x32, bf16_t* x16, int lane) {
; #pragma unroll
;   for (int j = 0; j < 4; ++j) {
;     *(uint2*)(x16 + j * 256 + lane * 4) = make_uint2(pack2(v[j].x, v[j].y), pack2(v[j].z, v[j].w));
;   }
; }
; DEVI float4 resid_plus(const uint2 xb, const uint2 mb) {
;   return make_float4(lo2f(xb.x) * DN_ALPHA + lo2f(mb.x), hi2f(xb.x) * DN_ALPHA + hi2f(mb.x), lo2f(xb.y) * DN_ALPHA + lo2f(mb.y), hi2f(xb.y) * DN_ALPHA + hi2f(mb.y));
; DEVI void phase_p7(const int TIDX, const int BIDX, const int GDIM, KAP KA, unsigned char* WSB, float* OUTB, int l, unsigned char* smem) {
;     ...
;       for (int t = 0; t < 4; ++t) {
;         const size_t row = (size_t)r4 * 4 + t;
; #pragma unroll
;         for (int j = 0; j < 4; ++j) v[t][j] = resid_plus(*(const uint2*)(XB + row * 1024 + j * 256 + lane * 4), *(const uint2*)((const bf16_t*)PRE + row * 1024 + j * 256 + lane * 4));
;         ln_inplace(v[t], g1, b1, lane);
;         store_row(v[t], OUTB + row * 1024, XB + row * 1024, lane);
	s_nop 0
	v_mul_f32_e32 v10, 0x4b800000, v69
	v_cmp_gt_f32_e32 vcc, s60, v69
	v_mul_f32_e32 v33, 0x4b800000, v68
	s_nop 0
	v_cndmask_b32_e32 v10, v69, v10, vcc
	v_rsq_f32_e32 v18, v10
	v_mov_b32_e32 v10, v19
	v_mul_f32_e32 v19, 0x45800000, v18
	v_cndmask_b32_e32 v18, v18, v19, vcc
	v_pk_mul_f32 v[22:23], v[48:49], v[18:19] op_sel_hi:[1,0]
	v_cmp_gt_f32_e32 vcc, s60, v68
	v_pk_fma_f32 v[24:25], v[100:101], v[22:23], v[102:103]
	v_pk_mul_f32 v[22:23], v[50:51], v[18:19] op_sel_hi:[1,0]
	v_cndmask_b32_e32 v33, v68, v33, vcc
	v_pk_fma_f32 v[26:27], v[0:1], v[22:23], v[4:5]
	v_pk_mul_f32 v[0:1], v[52:53], v[18:19] op_sel_hi:[1,0]
	v_rsq_f32_e32 v33, v33
	v_pk_fma_f32 v[28:29], v[28:29], v[0:1], v[104:105]
	v_pk_mul_f32 v[0:1], v[92:93], v[18:19] op_sel_hi:[1,0]
	s_nop 0
	v_pk_fma_f32 v[30:31], v[2:3], v[0:1], v[6:7]
	v_pk_mul_f32 v[0:1], v[94:95], v[18:19] op_sel_hi:[1,0]
	s_nop 0
	v_pk_fma_f32 v[46:47], v[0:1], v[106:107], v[108:109]
	v_pk_mul_f32 v[0:1], v[96:97], v[18:19] op_sel_hi:[1,0]
	s_nop 0
	v_pk_fma_f32 v[48:49], v[0:1], v[8:9], v[12:13]
	v_pk_mul_f32 v[0:1], v[90:91], v[18:19] op_sel_hi:[1,0]
	s_nop 0
	v_pk_fma_f32 v[50:51], v[0:1], v[110:111], v[112:113]
	v_pk_mul_f32 v[0:1], v[98:99], v[18:19] op_sel_hi:[1,0]
	v_or_b32_e32 v18, 0x1000, v70
	v_pk_fma_f32 v[52:53], v[0:1], v[10:11], v[14:15]
	v_cvt_pk_bf16_f32 v0, v24, v26
	v_cvt_pk_bf16_f32 v1, v28, v30
	global_store_dwordx2 v[54:55], v[0:1], off
	v_cvt_pk_bf16_f32 v0, v25, v27
	v_cvt_pk_bf16_f32 v1, v29, v31
	global_store_dwordx2 v[54:55], v[0:1], off offset:512
	v_cvt_pk_bf16_f32 v0, v46, v48
	v_cvt_pk_bf16_f32 v1, v50, v52
	global_store_dwordx2 v[54:55], v[0:1], off offset:1024
	v_cvt_pk_bf16_f32 v0, v47, v49
	v_cvt_pk_bf16_f32 v1, v51, v53
	global_store_dwordx2 v[54:55], v[0:1], off offset:1536
	global_load_dwordx4 v[0:3], v[38:39], off
	s_nop 0
	global_load_dwordx4 v[4:7], v[38:39], off offset:1024
	global_load_dwordx4 v[8:11], v[40:41], off
	global_load_dwordx4 v[12:15], v[40:41], off offset:1024
	global_load_dwordx4 v[78:81], v[38:39], off offset:2048
	global_load_dwordx4 v[90:93], v[38:39], off offset:3072
	global_load_dwordx4 v[94:97], v[40:41], off offset:2048
	global_load_dwordx4 v[98:101], v[40:41], off offset:3072
	v_mov_b32_e32 v19, v71
	v_lshl_add_u64 v[74:75], v[34:35], 0, v[18:19]
	v_lshl_add_u64 v[18:19], v[36:37], 0, v[18:19]
	global_load_dwordx2 v[22:23], v[74:75], off offset:1024
	global_load_dwordx2 v[102:103], v[74:75], off offset:1536
	global_load_dwordx2 v[104:105], v[18:19], off offset:1536
	global_load_dwordx2 v[106:107], v[18:19], off offset:1024
	global_load_dwordx2 v[108:109], v[74:75], off
	global_load_dwordx2 v[110:111], v[74:75], off offset:512
	global_load_dwordx2 v[112:113], v[18:19], off
	global_load_dwordx2 v[114:115], v[18:19], off offset:512
	v_mul_f32_e32 v18, 0x45800000, v33
	v_cndmask_b32_e32 v18, v33, v18, vcc
	v_pk_mul_f32 v[54:55], v[66:67], v[18:19] op_sel_hi:[1,0]
	v_pk_mul_f32 v[56:57], v[56:57], v[18:19] op_sel_hi:[1,0]
	v_or_b32_e32 v70, 0x1800, v70
	s_waitcnt vmcnt(15)
	v_mov_b32_e32 v66, v0
	s_waitcnt vmcnt(14)
	v_mov_b32_e32 v67, v4
	v_mov_b32_e32 v4, v1
	s_waitcnt vmcnt(12)
	v_mov_b32_e32 v69, v12
	v_mov_b32_e32 v12, v9
	v_mov_b32_e32 v68, v8
	v_pk_fma_f32 v[56:57], v[4:5], v[56:57], v[12:13]
	v_pk_mul_f32 v[0:1], v[58:59], v[18:19] op_sel_hi:[1,0]
	v_mov_b32_e32 v4, v2
	v_mov_b32_e32 v5, v6
	v_mov_b32_e32 v8, v10
	v_mov_b32_e32 v9, v14
	v_pk_fma_f32 v[58:59], v[4:5], v[0:1], v[8:9]
	v_pk_mul_f32 v[0:1], v[60:61], v[18:19] op_sel_hi:[1,0]
	v_mov_b32_e32 v6, v3
	v_mov_b32_e32 v14, v11
	v_pk_fma_f32 v[60:61], v[6:7], v[0:1], v[14:15]
	v_pk_mul_f32 v[0:1], v[62:63], v[18:19] op_sel_hi:[1,0]
	s_waitcnt vmcnt(11)
	v_mov_b32_e32 v2, v78
	s_waitcnt vmcnt(10)
	v_mov_b32_e32 v3, v90
	s_waitcnt vmcnt(9)
	v_mov_b32_e32 v4, v94
	s_waitcnt vmcnt(8)
	v_mov_b32_e32 v5, v98
	v_pk_fma_f32 v[62:63], v[0:1], v[2:3], v[4:5]
	v_pk_mul_f32 v[0:1], v[64:65], v[18:19] op_sel_hi:[1,0]
	v_mov_b32_e32 v90, v79
	v_mov_b32_e32 v98, v95
	v_pk_fma_f32 v[64:65], v[0:1], v[90:91], v[98:99]
	v_pk_mul_f32 v[0:1], v[20:21], v[18:19] op_sel_hi:[1,0]
	v_mov_b32_e32 v2, v80
	v_mov_b32_e32 v3, v92
	v_mov_b32_e32 v4, v96
	v_mov_b32_e32 v5, v100
	v_pk_fma_f32 v[54:55], v[66:67], v[54:55], v[68:69]
	v_pk_fma_f32 v[66:67], v[0:1], v[2:3], v[4:5]
	v_pk_mul_f32 v[0:1], v[16:17], v[18:19] op_sel_hi:[1,0]
	v_mov_b32_e32 v92, v81
	v_mov_b32_e32 v100, v97
	v_pk_fma_f32 v[68:69], v[0:1], v[92:93], v[100:101]
	v_cvt_pk_bf16_f32 v0, v54, v56
	v_cvt_pk_bf16_f32 v1, v58, v60
	global_store_dwordx2 v[76:77], v[0:1], off
	v_cvt_pk_bf16_f32 v0, v55, v57
	v_cvt_pk_bf16_f32 v1, v59, v61
	global_store_dwordx2 v[76:77], v[0:1], off offset:512
	v_cvt_pk_bf16_f32 v0, v62, v64
	v_cvt_pk_bf16_f32 v1, v66, v68
	global_store_dwordx2 v[76:77], v[0:1], off offset:1024
	v_cvt_pk_bf16_f32 v0, v63, v65
	v_cvt_pk_bf16_f32 v1, v67, v69
	global_store_dwordx2 v[76:77], v[0:1], off offset:1536
	s_waitcnt vmcnt(10)
	v_lshlrev_b32_e32 v1, 16, v102
	v_lshlrev_b32_e32 v0, 16, v22
	s_waitcnt vmcnt(9)
	v_lshlrev_b32_e32 v3, 16, v104
	s_waitcnt vmcnt(8)
	v_lshlrev_b32_e32 v2, 16, v106
	v_pk_fma_f32 v[76:77], v[0:1], s[64:65], v[2:3] op_sel_hi:[1,0,1]
	v_and_b32_e32 v1, 0xffff0000, v102
	v_and_b32_e32 v0, 0xffff0000, v22
	v_and_b32_e32 v3, 0xffff0000, v104
	v_and_b32_e32 v2, 0xffff0000, v106
	v_pk_fma_f32 v[78:79], v[0:1], s[64:65], v[2:3] op_sel_hi:[1,0,1]
	v_lshlrev_b32_e32 v1, 16, v103
	v_lshlrev_b32_e32 v0, 16, v23
	v_lshlrev_b32_e32 v3, 16, v105
	v_lshlrev_b32_e32 v2, 16, v107
	v_pk_fma_f32 v[82:83], v[0:1], s[64:65], v[2:3] op_sel_hi:[1,0,1]
	v_and_b32_e32 v1, 0xffff0000, v103
	v_and_b32_e32 v0, 0xffff0000, v23
	v_and_b32_e32 v3, 0xffff0000, v105
	v_and_b32_e32 v2, 0xffff0000, v107
	v_pk_fma_f32 v[98:99], v[0:1], s[64:65], v[2:3] op_sel_hi:[1,0,1]
	v_pk_add_f32 v[0:1], v[76:77], v[78:79]
	s_waitcnt vmcnt(4)
; DEVI uint32_t pack2(float lo, float hi) { f32x2_t v = {lo, hi}; bf16x2_t b = __builtin_convertvector(v, bf16x2_t); return __builtin_bit_cast(uint32_t, b); }
; DEVI float lo2f(uint32_t u) { return __uint_as_float(u << 16); }
; DEVI float hi2f(uint32_t u) { return __uint_as_float(u & 0xffff0000u); }
; DEVI void ln_inplace(float4 (&v)[4], const float* __restrict__ g, const float* __restrict__ b, int lane) {
;   float s = 0.f;
; #pragma unroll
;   for (int j = 0; j < 4; ++j) s += v[j].x + v[j].y + v[j].z + v[j].w;
;   s = wave_sum(s);
;   const float mu = s * (1.f / 1024.f);
;   float q = 0.f;
; #pragma unroll
;   for (int j = 0; j < 4; ++j) {
;     float a = v[j].x - mu, bq = v[j].y - mu, cq = v[j].z - mu, d = v[j].w - mu;
;     q += a * a + bq * bq + cq * cq + d * d;
;   }
;   q = wave_sum(q);
;   const float rs = rsqrtf(q * (1.f / 1024.f) + EPS);
; #pragma unroll
;   for (int j = 0; j < 4; ++j) {
;     const float4 gg = *(const float4*)(g + j * 256 + lane * 4), bb = *(const float4*)(b + j * 256 + lane * 4);
;     v[j].x = (v[j].x - mu) * rs * gg.x + bb.x;
;     v[j].y = (v[j].y - mu) * rs * gg.y + bb.y;
;     v[j].z = (v[j].z - mu) * rs * gg.z + bb.z;
;     v[j].w = (v[j].w - mu) * rs * gg.w + bb.w;
;   }
; }
; DEVI void store_row(const float4 (&v)[4], float* x32, bf16_t* x16, int lane) {
; #pragma unroll
;   for (int j = 0; j < 4; ++j) {
;     *(uint2*)(x16 + j * 256 + lane * 4) = make_uint2(pack2(v[j].x, v[j].y), pack2(v[j].z, v[j].w));
;   }
; }
; DEVI float4 resid_plus(const uint2 xb, const uint2 mb) {
;   return make_float4(lo2f(xb.x) * DN_ALPHA + lo2f(mb.x), hi2f(xb.x) * DN_ALPHA + hi2f(mb.x), lo2f(xb.y) * DN_ALPHA + lo2f(mb.y), hi2f(xb.y) * DN_ALPHA + hi2f(mb.y));
; DEVI void phase_p7(const int TIDX, const int BIDX, const int GDIM, KAP KA, unsigned char* WSB, float* OUTB, int l, unsigned char* smem) {
;     ...
;       for (int t = 0; t < 4; ++t) {
;         const size_t row = (size_t)r4 * 4 + t;
; #pragma unroll
;         for (int j = 0; j < 4; ++j) v[t][j] = resid_plus(*(const uint2*)(XB + row * 1024 + j * 256 + lane * 4), *(const uint2*)((const bf16_t*)PRE + row * 1024 + j * 256 + lane * 4));
;         ln_inplace(v[t], g1, b1, lane);
;         store_row(v[t], OUTB + row * 1024, XB + row * 1024, lane);
	v_lshlrev_b32_e32 v3, 16, v114
	v_pk_add_f32 v[0:1], v[0:1], v[82:83]
	v_lshlrev_b32_e32 v2, 16, v112
	v_pk_add_f32 v[100:101], v[98:99], v[0:1]
	v_lshlrev_b32_e32 v1, 16, v110
	v_lshlrev_b32_e32 v0, 16, v108
	v_and_b32_e32 v9, 0xffff0000, v110
	v_and_b32_e32 v8, 0xffff0000, v108
	v_and_b32_e32 v11, 0xffff0000, v114
	v_and_b32_e32 v10, 0xffff0000, v112
	v_pk_fma_f32 v[102:103], v[0:1], s[64:65], v[2:3] op_sel_hi:[1,0,1]
	v_pk_fma_f32 v[104:105], v[8:9], s[64:65], v[10:11] op_sel_hi:[1,0,1]
	v_lshlrev_b32_e32 v9, 16, v111
	v_lshlrev_b32_e32 v8, 16, v109
	v_lshlrev_b32_e32 v11, 16, v115
	v_lshlrev_b32_e32 v10, 16, v113
	v_and_b32_e32 v111, 0xffff0000, v111
	v_and_b32_e32 v110, 0xffff0000, v109
	v_and_b32_e32 v109, 0xffff0000, v115
	v_and_b32_e32 v108, 0xffff0000, v113
	v_pk_fma_f32 v[106:107], v[8:9], s[64:65], v[10:11] op_sel_hi:[1,0,1]
	v_pk_fma_f32 v[108:109], v[110:111], s[64:65], v[108:109] op_sel_hi:[1,0,1]
	v_pk_add_f32 v[110:111], v[102:103], v[104:105]
	v_lshl_add_u64 v[80:81], v[34:35], 0, v[70:71]
	v_pk_add_f32 v[110:111], v[110:111], v[106:107]
	global_load_dwordx4 v[90:93], v[38:39], off
	global_load_dwordx4 v[0:3], v[38:39], off offset:1024
	global_load_dwordx4 v[94:97], v[40:41], off
	global_load_dwordx4 v[4:7], v[40:41], off offset:1024
	global_load_dwordx4 v[16:19], v[38:39], off offset:2048
	global_load_dwordx4 v[8:11], v[38:39], off offset:3072
	global_load_dwordx4 v[20:23], v[40:41], off offset:2048
	global_load_dwordx4 v[12:15], v[40:41], off offset:3072
	v_lshl_add_u64 v[70:71], v[36:37], 0, v[70:71]
	global_load_dwordx2 v[114:115], v[80:81], off offset:1024
	global_load_dwordx2 v[116:117], v[80:81], off offset:1536
	global_load_dwordx2 v[118:119], v[70:71], off offset:1024
	global_load_dwordx2 v[120:121], v[70:71], off offset:1536
	v_pk_add_f32 v[110:111], v[108:109], v[110:111]
	s_waitcnt vmcnt(9)
	v_mov_b32_e32 v126, v94
	v_add_f32_e32 v33, 0, v110
	v_add_f32_e32 v33, v33, v111
	global_load_dwordx2 v[110:111], v[80:81], off
	global_load_dwordx2 v[112:113], v[80:81], off offset:512
	global_load_dwordx2 v[122:123], v[70:71], off
	s_nop 0
	global_load_dwordx2 v[70:71], v[70:71], off offset:512
	v_add_f32_e32 v33, v33, v100
	v_add_f32_e32 v33, v33, v101
	s_waitcnt vmcnt(4)
	v_lshlrev_b32_e32 v135, 16, v120
	v_lshlrev_b32_e32 v134, 16, v118
	v_add_f32_dpp v33, v33, v33 quad_perm:[1,0,3,2] row_mask:0xf bank_mask:0xf bound_ctrl:1
	v_and_b32_e32 v137, 0xffff0000, v120
	v_and_b32_e32 v136, 0xffff0000, v118
	v_add_f32_dpp v33, v33, v33 quad_perm:[2,3,0,1] row_mask:0xf bank_mask:0xf bound_ctrl:1
	v_lshlrev_b32_e32 v139, 16, v121
	v_lshlrev_b32_e32 v138, 16, v119
	v_add_f32_dpp v33, v33, v33 row_half_mirror row_mask:0xf bank_mask:0xf bound_ctrl:1
	v_mov_b32_e32 v127, v4
	v_mov_b32_e32 v4, v95
	v_add_f32_dpp v33, v33, v33 row_mirror row_mask:0xf bank_mask:0xf bound_ctrl:1
	v_mov_b32_e32 v95, v6
	v_readlane_b32 s2, v33, 16
	v_readlane_b32 s3, v33, 48
	v_readlane_b32 s0, v33, 0
	v_readlane_b32 s1, v33, 32
	v_mov_b32_e32 v100, s2
	v_mov_b32_e32 v101, s3
	v_pk_add_f32 v[100:101], s[0:1], v[100:101]
	v_mov_b32_e32 v6, v97
	v_add_f32_e32 v33, v100, v101
	v_mul_f32_e32 v100, 0x3a800000, v33
	v_pk_add_f32 v[104:105], v[104:105], v[100:101] op_sel_hi:[1,0] neg_lo:[0,1] neg_hi:[0,1]
	v_pk_add_f32 v[102:103], v[102:103], v[100:101] op_sel_hi:[1,0] neg_lo:[0,1] neg_hi:[0,1]
	v_pk_mul_f32 v[124:125], v[104:105], v[104:105]
	v_pk_add_f32 v[106:107], v[106:107], v[100:101] op_sel_hi:[1,0] neg_lo:[0,1] neg_hi:[0,1]
	v_pk_fma_f32 v[124:125], v[102:103], v[102:103], v[124:125]
	v_pk_add_f32 v[108:109], v[108:109], v[100:101] op_sel_hi:[1,0] neg_lo:[0,1] neg_hi:[0,1]
	v_pk_fma_f32 v[124:125], v[106:107], v[106:107], v[124:125]
	v_pk_add_f32 v[78:79], v[78:79], v[100:101] op_sel_hi:[1,0] neg_lo:[0,1] neg_hi:[0,1]
	v_pk_fma_f32 v[124:125], v[108:109], v[108:109], v[124:125]
	v_pk_add_f32 v[76:77], v[76:77], v[100:101] op_sel_hi:[1,0] neg_lo:[0,1] neg_hi:[0,1]
	v_add_f32_e32 v33, v124, v125
	v_mov_b32_e32 v124, v90
	v_mov_b32_e32 v125, v0
	v_mov_b32_e32 v0, v91
	v_mov_b32_e32 v90, v92
	v_mov_b32_e32 v91, v2
	v_mov_b32_e32 v2, v93
	v_mov_b32_e32 v92, v16
	v_mov_b32_e32 v93, v8
	v_mov_b32_e32 v8, v17
	v_lshlrev_b32_e32 v17, 16, v116
	v_lshlrev_b32_e32 v16, 16, v114
	v_pk_fma_f32 v[16:17], v[16:17], s[64:65], v[134:135] op_sel_hi:[1,0,1]
	v_and_b32_e32 v135, 0xffff0000, v116
	v_and_b32_e32 v134, 0xffff0000, v114
	v_pk_fma_f32 v[134:135], v[134:135], s[64:65], v[136:137] op_sel_hi:[1,0,1]
	v_lshlrev_b32_e32 v137, 16, v117
	v_lshlrev_b32_e32 v136, 16, v115
	v_and_b32_e32 v116, 0xffff0000, v115
	v_and_b32_e32 v115, 0xffff0000, v121
	v_and_b32_e32 v114, 0xffff0000, v119
	v_pk_fma_f32 v[136:137], v[136:137], s[64:65], v[138:139] op_sel_hi:[1,0,1]
	v_pk_add_f32 v[82:83], v[82:83], v[100:101] op_sel_hi:[1,0] neg_lo:[0,1] neg_hi:[0,1]
	v_pk_add_f32 v[98:99], v[98:99], v[100:101] op_sel_hi:[1,0] neg_lo:[0,1] neg_hi:[0,1]
	v_pk_mul_f32 v[100:101], v[78:79], v[78:79]
	v_and_b32_e32 v117, 0xffff0000, v117
	v_pk_fma_f32 v[100:101], v[76:77], v[76:77], v[100:101]
	v_pk_fma_f32 v[114:115], v[116:117], s[64:65], v[114:115] op_sel_hi:[1,0,1]
	v_pk_fma_f32 v[100:101], v[82:83], v[82:83], v[100:101]
	v_pk_add_f32 v[116:117], v[16:17], v[134:135]
	v_pk_fma_f32 v[100:101], v[98:99], v[98:99], v[100:101]
	v_mov_b32_e32 v97, v12
	v_mov_b32_e32 v12, v21
	v_mov_b32_e32 v21, v10
	v_pk_add_f32 v[116:117], v[116:117], v[136:137]
	v_add_f32_e32 v33, v100, v33
	v_pk_add_f32 v[116:117], v[114:115], v[116:117]
	v_add_f32_e32 v33, v101, v33
	v_mov_b32_e32 v132, v22
	v_mov_b32_e32 v94, v96
	v_add_f32_dpp v33, v33, v33 quad_perm:[1,0,3,2] row_mask:0xf bank_mask:0xf bound_ctrl:1
	s_waitcnt vmcnt(3)
; DEVI uint32_t pack2(float lo, float hi) { f32x2_t v = {lo, hi}; bf16x2_t b = __builtin_convertvector(v, bf16x2_t); return __builtin_bit_cast(uint32_t, b); }
; DEVI float lo2f(uint32_t u) { return __uint_as_float(u << 16); }
; DEVI float hi2f(uint32_t u) { return __uint_as_float(u & 0xffff0000u); }
; DEVI void ln_inplace(float4 (&v)[4], const float* __restrict__ g, const float* __restrict__ b, int lane) {
;   float s = 0.f;
; #pragma unroll
;   for (int j = 0; j < 4; ++j) s += v[j].x + v[j].y + v[j].z + v[j].w;
;   s = wave_sum(s);
;   const float mu = s * (1.f / 1024.f);
;   float q = 0.f;
; #pragma unroll
;   for (int j = 0; j < 4; ++j) {
;     float a = v[j].x - mu, bq = v[j].y - mu, cq = v[j].z - mu, d = v[j].w - mu;
;     q += a * a + bq * bq + cq * cq + d * d;
;   }
;   q = wave_sum(q);
;   const float rs = rsqrtf(q * (1.f / 1024.f) + EPS);
; #pragma unroll
;   for (int j = 0; j < 4; ++j) {
;     const float4 gg = *(const float4*)(g + j * 256 + lane * 4), bb = *(const float4*)(b + j * 256 + lane * 4);
;     v[j].x = (v[j].x - mu) * rs * gg.x + bb.x;
;     v[j].y = (v[j].y - mu) * rs * gg.y + bb.y;
;     v[j].z = (v[j].z - mu) * rs * gg.z + bb.z;
;     v[j].w = (v[j].w - mu) * rs * gg.w + bb.w;
;   }
; }
; DEVI void store_row(const float4 (&v)[4], float* x32, bf16_t* x16, int lane) {
; #pragma unroll
;   for (int j = 0; j < 4; ++j) {
;     *(uint2*)(x16 + j * 256 + lane * 4) = make_uint2(pack2(v[j].x, v[j].y), pack2(v[j].z, v[j].w));
;   }
; }
; DEVI float4 resid_plus(const uint2 xb, const uint2 mb) {
;   return make_float4(lo2f(xb.x) * DN_ALPHA + lo2f(mb.x), hi2f(xb.x) * DN_ALPHA + hi2f(mb.x), lo2f(xb.y) * DN_ALPHA + lo2f(mb.y), hi2f(xb.y) * DN_ALPHA + hi2f(mb.y));
; DEVI void phase_p7(const int TIDX, const int BIDX, const int GDIM, KAP KA, unsigned char* WSB, float* OUTB, int l, unsigned char* smem) {
;     ...
;       for (int t = 0; t < 4; ++t) {
;         const size_t row = (size_t)r4 * 4 + t;
; #pragma unroll
;         for (int j = 0; j < 4; ++j) v[t][j] = resid_plus(*(const uint2*)(XB + row * 1024 + j * 256 + lane * 4), *(const uint2*)((const bf16_t*)PRE + row * 1024 + j * 256 + lane * 4));
;         ln_inplace(v[t], g1, b1, lane);
;         store_row(v[t], OUTB + row * 1024, XB + row * 1024, lane);
	v_lshlrev_b32_e32 v118, 16, v110
	s_waitcnt vmcnt(2)
	v_lshlrev_b32_e32 v119, 16, v112
	s_waitcnt vmcnt(1)
	v_lshlrev_b32_e32 v120, 16, v122
	s_waitcnt vmcnt(0)
	v_lshlrev_b32_e32 v121, 16, v70
	v_pk_fma_f32 v[118:119], v[118:119], s[64:65], v[120:121] op_sel_hi:[1,0,1]
	v_and_b32_e32 v121, 0xffff0000, v112
	v_and_b32_e32 v120, 0xffff0000, v110
	v_and_b32_e32 v139, 0xffff0000, v70
	v_and_b32_e32 v138, 0xffff0000, v122
	v_pk_fma_f32 v[120:121], v[120:121], s[64:65], v[138:139] op_sel_hi:[1,0,1]
	v_lshlrev_b32_e32 v139, 16, v113
	v_lshlrev_b32_e32 v138, 16, v111
	v_lshlrev_b32_e32 v141, 16, v71
	v_lshlrev_b32_e32 v140, 16, v123
	v_pk_fma_f32 v[138:139], v[138:139], s[64:65], v[140:141] op_sel_hi:[1,0,1]
	v_and_b32_e32 v113, 0xffff0000, v113
	v_and_b32_e32 v112, 0xffff0000, v111
	v_and_b32_e32 v71, 0xffff0000, v71
	v_and_b32_e32 v70, 0xffff0000, v123
	v_pk_add_f32 v[110:111], v[118:119], v[120:121]
	v_pk_fma_f32 v[70:71], v[112:113], s[64:65], v[70:71] op_sel_hi:[1,0,1]
	v_pk_add_f32 v[110:111], v[110:111], v[138:139]
	v_add_f32_dpp v33, v33, v33 quad_perm:[2,3,0,1] row_mask:0xf bank_mask:0xf bound_ctrl:1
	v_pk_add_f32 v[110:111], v[70:71], v[110:111]
	v_mov_b32_e32 v96, v20
	v_add_f32_e32 v10, 0, v110
	v_add_f32_e32 v10, v10, v111
	v_add_f32_e32 v10, v10, v116
	v_add_f32_e32 v10, v10, v117
	v_add_f32_dpp v33, v33, v33 row_half_mirror row_mask:0xf bank_mask:0xf bound_ctrl:1
	v_mov_b32_e32 v20, v18
	v_add_f32_dpp v10, v10, v10 quad_perm:[1,0,3,2] row_mask:0xf bank_mask:0xf bound_ctrl:1
	v_add_f32_dpp v33, v33, v33 row_mirror row_mask:0xf bank_mask:0xf bound_ctrl:1
	v_mov_b32_e32 v133, v14
	v_add_f32_dpp v10, v10, v10 quad_perm:[2,3,0,1] row_mask:0xf bank_mask:0xf bound_ctrl:1
	v_readlane_b32 s2, v33, 16
	v_readlane_b32 s3, v33, 48
	v_add_f32_dpp v10, v10, v10 row_half_mirror row_mask:0xf bank_mask:0xf bound_ctrl:1
	v_readlane_b32 s0, v33, 0
	v_readlane_b32 s1, v33, 32
	v_add_f32_dpp v10, v10, v10 row_mirror row_mask:0xf bank_mask:0xf bound_ctrl:1
	v_mov_b32_e32 v100, s2
	v_mov_b32_e32 v101, s3
	v_readlane_b32 s2, v10, 16
	v_readlane_b32 s3, v10, 48
	v_pk_add_f32 v[100:101], s[0:1], v[100:101]
	v_readlane_b32 s0, v10, 0
	v_readlane_b32 s1, v10, 32
	v_mov_b32_e32 v110, s2
	v_mov_b32_e32 v111, s3
	v_pk_add_f32 v[110:111], s[0:1], v[110:111]
	v_mov_b32_e32 v14, v23
	v_add_f32_e32 v10, v110, v111
	v_mul_f32_e32 v10, 0x3a800000, v10
	v_pk_add_f32 v[116:117], v[118:119], v[10:11] op_sel_hi:[1,0] neg_lo:[0,1] neg_hi:[0,1]
	v_pk_add_f32 v[118:119], v[120:121], v[10:11] op_sel_hi:[1,0] neg_lo:[0,1] neg_hi:[0,1]
	v_pk_add_f32 v[122:123], v[70:71], v[10:11] op_sel_hi:[1,0] neg_lo:[0,1] neg_hi:[0,1]
	v_pk_mul_f32 v[70:71], v[118:119], v[118:119]
	v_pk_add_f32 v[134:135], v[134:135], v[10:11] op_sel_hi:[1,0] neg_lo:[0,1] neg_hi:[0,1]
	v_pk_add_f32 v[120:121], v[138:139], v[10:11] op_sel_hi:[1,0] neg_lo:[0,1] neg_hi:[0,1]
	v_pk_fma_f32 v[70:71], v[116:117], v[116:117], v[70:71]
	v_pk_add_f32 v[138:139], v[16:17], v[10:11] op_sel_hi:[1,0] neg_lo:[0,1] neg_hi:[0,1]
	v_pk_mul_f32 v[16:17], v[134:135], v[134:135]
	v_pk_fma_f32 v[70:71], v[120:121], v[120:121], v[70:71]
	v_pk_add_f32 v[136:137], v[136:137], v[10:11] op_sel_hi:[1,0] neg_lo:[0,1] neg_hi:[0,1]
	v_pk_fma_f32 v[16:17], v[138:139], v[138:139], v[16:17]
	v_pk_fma_f32 v[70:71], v[122:123], v[122:123], v[70:71]
	v_pk_add_f32 v[114:115], v[114:115], v[10:11] op_sel_hi:[1,0] neg_lo:[0,1] neg_hi:[0,1]
	v_pk_fma_f32 v[16:17], v[136:137], v[136:137], v[16:17]
	v_add_f32_e32 v10, v70, v71
	v_pk_fma_f32 v[16:17], v[114:115], v[114:115], v[16:17]
	v_mov_b32_e32 v71, v100
	v_add_f32_e32 v10, v16, v10
	v_add_f32_e32 v10, v17, v10
	v_mov_b32_e32 v33, 0
	s_nop 0
	v_add_f32_dpp v10, v10, v10 quad_perm:[1,0,3,2] row_mask:0xf bank_mask:0xf bound_ctrl:1
	s_nop 1
	v_add_f32_dpp v10, v10, v10 quad_perm:[2,3,0,1] row_mask:0xf bank_mask:0xf bound_ctrl:1
	s_nop 1
	v_add_f32_dpp v10, v10, v10 row_half_mirror row_mask:0xf bank_mask:0xf bound_ctrl:1
	s_nop 1
	v_add_f32_dpp v10, v10, v10 row_mirror row_mask:0xf bank_mask:0xf bound_ctrl:1
	s_nop 0
	v_readlane_b32 s2, v10, 16
	v_readlane_b32 s3, v10, 48
	v_readlane_b32 s0, v10, 0
	v_readlane_b32 s1, v10, 32
	v_mov_b32_e32 v16, s2
	v_mov_b32_e32 v17, s3
	v_pk_add_f32 v[16:17], s[0:1], v[16:17]
	s_mov_b32 s2, 0
	v_mov_b32_e32 v70, v16
	v_mov_b32_e32 v100, v17
	v_pk_add_f32 v[16:17], v[70:71], v[100:101]
	s_mov_b64 s[0:1], 0
	v_pk_fma_f32 v[140:141], v[16:17], s[22:23], v[72:73] op_sel_hi:[1,0,0]
	s_nop 0
	v_mul_f32_e32 v10, 0x4b800000, v141
	v_cmp_gt_f32_e32 vcc, s60, v141
	s_nop 1
	v_cndmask_b32_e32 v10, v141, v10, vcc
	v_rsq_f32_e32 v16, v10
	v_mov_b32_e32 v10, v19
	v_mul_f32_e32 v17, 0x45800000, v16
	v_cndmask_b32_e32 v22, v16, v17, vcc
	v_pk_mul_f32 v[18:19], v[104:105], v[22:23] op_sel_hi:[1,0]
	v_pk_mul_f32 v[16:17], v[102:103], v[22:23] op_sel_hi:[1,0]
	v_pk_fma_f32 v[4:5], v[0:1], v[18:19], v[4:5]
	v_pk_mul_f32 v[0:1], v[106:107], v[22:23] op_sel_hi:[1,0]
	v_pk_fma_f32 v[16:17], v[124:125], v[16:17], v[126:127]
	v_pk_fma_f32 v[18:19], v[90:91], v[0:1], v[94:95]
	v_pk_mul_f32 v[0:1], v[108:109], v[22:23] op_sel_hi:[1,0]
	v_cmp_gt_f32_e32 vcc, s60, v140
	v_pk_fma_f32 v[2:3], v[2:3], v[0:1], v[6:7]
	v_pk_mul_f32 v[0:1], v[76:77], v[22:23] op_sel_hi:[1,0]
	s_nop 0
	v_pk_fma_f32 v[6:7], v[0:1], v[92:93], v[96:97]
	v_pk_mul_f32 v[0:1], v[78:79], v[22:23] op_sel_hi:[1,0]
	s_nop 0
	v_pk_fma_f32 v[8:9], v[0:1], v[8:9], v[12:13]
	v_pk_mul_f32 v[0:1], v[82:83], v[22:23] op_sel_hi:[1,0]
	v_mov_b32_e32 v82, 0
	v_pk_fma_f32 v[12:13], v[0:1], v[20:21], v[132:133]
	v_pk_mul_f32 v[0:1], v[98:99], v[22:23] op_sel_hi:[1,0]
	s_nop 0
	v_pk_fma_f32 v[10:11], v[0:1], v[10:11], v[14:15]
	v_cvt_pk_bf16_f32 v0, v16, v4
	v_cvt_pk_bf16_f32 v1, v18, v2
	global_store_dwordx2 v[74:75], v[0:1], off
	v_cvt_pk_bf16_f32 v0, v17, v5
	v_cvt_pk_bf16_f32 v1, v19, v3
	global_store_dwordx2 v[74:75], v[0:1], off offset:512
	v_cvt_pk_bf16_f32 v0, v6, v8
	v_cvt_pk_bf16_f32 v1, v12, v10
	global_store_dwordx2 v[74:75], v[0:1], off offset:1024
	v_cvt_pk_bf16_f32 v0, v7, v9
	v_cvt_pk_bf16_f32 v1, v13, v11
	global_store_dwordx2 v[74:75], v[0:1], off offset:1536
	global_load_dwordx4 v[70:73], v[38:39], off
	s_nop 0
	global_load_dwordx4 v[74:77], v[38:39], off offset:1024
	global_load_dwordx4 v[90:93], v[40:41], off
	global_load_dwordx4 v[94:97], v[40:41], off offset:1024
	global_load_dwordx4 v[98:101], v[38:39], off offset:2048
	global_load_dwordx4 v[102:105], v[38:39], off offset:3072
	global_load_dwordx4 v[106:109], v[40:41], off offset:2048
	global_load_dwordx4 v[110:113], v[40:41], off offset:3072
	v_mul_f32_e32 v0, 0x4b800000, v140
	v_cndmask_b32_e32 v0, v140, v0, vcc
	v_rsq_f32_e32 v0, v0
	s_waitcnt vmcnt(7)
; DEVI uint32_t pack2(float lo, float hi) { f32x2_t v = {lo, hi}; bf16x2_t b = __builtin_convertvector(v, bf16x2_t); return __builtin_bit_cast(uint32_t, b); }
; DEVI void ln_inplace(float4 (&v)[4], const float* __restrict__ g, const float* __restrict__ b, int lane) {
;     ...
;   for (int j = 0; j < 4; ++j) {
;     const float4 gg = *(const float4*)(g + j * 256 + lane * 4), bb = *(const float4*)(b + j * 256 + lane * 4);
;     v[j].x = (v[j].x - mu) * rs * gg.x + bb.x;
;     v[j].y = (v[j].y - mu) * rs * gg.y + bb.y;
;     v[j].z = (v[j].z - mu) * rs * gg.z + bb.z;
;     v[j].w = (v[j].w - mu) * rs * gg.w + bb.w;
;   }
; }
; DEVI void store_row(const float4 (&v)[4], float* x32, bf16_t* x16, int lane) {
; #pragma unroll
;   for (int j = 0; j < 4; ++j) {
;     *(uint2*)(x16 + j * 256 + lane * 4) = make_uint2(pack2(v[j].x, v[j].y), pack2(v[j].z, v[j].w));
;   }
; DEVI void phase_p7(const int TIDX, const int BIDX, const int GDIM, KAP KA, unsigned char* WSB, float* OUTB, int l, unsigned char* smem) {
;     ...
; #pragma unroll 4
;       for (int c = 0; c < 36; ++c) {
;         float4 wv[4];
; #pragma unroll
;         for (int j = 0; j < 4; ++j) wv[j] = *(const float4*)(WR + c * 1024 + j * 256 + lane * 4);
; #pragma unroll
;         for (int t = 0; t < 4; ++t) {
;           float s = 0.f;
; #pragma unroll
;           for (int j = 0; j < 4; ++j) s += v[t][j].x * wv[j].x + v[t][j].y * wv[j].y + v[t][j].z * wv[j].z + v[t][j].w * wv[j].w;
;           s = wave_sum(s);
;           if (lane == c) mine[t] = s;
;         }
	v_mov_b32_e32 v20, v70
	v_mul_f32_e32 v1, 0x45800000, v0
	v_cndmask_b32_e32 v0, v0, v1, vcc
	v_pk_mul_f32 v[14:15], v[116:117], v[0:1] op_sel_hi:[1,0]
	s_waitcnt vmcnt(6)
	v_mov_b32_e32 v21, v74
	s_waitcnt vmcnt(5)
	v_mov_b32_e32 v22, v90
	s_waitcnt vmcnt(4)
	v_mov_b32_e32 v23, v94
	v_pk_fma_f32 v[14:15], v[20:21], v[14:15], v[22:23]
	v_pk_mul_f32 v[20:21], v[118:119], v[0:1] op_sel_hi:[1,0]
	v_mov_b32_e32 v74, v71
	v_mov_b32_e32 v94, v91
	v_pk_fma_f32 v[20:21], v[74:75], v[20:21], v[94:95]
	v_pk_mul_f32 v[22:23], v[120:121], v[0:1] op_sel_hi:[1,0]
	v_mov_b32_e32 v70, v72
	v_mov_b32_e32 v71, v76
	v_mov_b32_e32 v74, v92
	v_mov_b32_e32 v75, v96
	v_pk_fma_f32 v[22:23], v[70:71], v[22:23], v[74:75]
	v_pk_mul_f32 v[70:71], v[122:123], v[0:1] op_sel_hi:[1,0]
	v_mov_b32_e32 v76, v73
	v_mov_b32_e32 v96, v93
	v_pk_fma_f32 v[70:71], v[76:77], v[70:71], v[96:97]
	v_pk_mul_f32 v[72:73], v[138:139], v[0:1] op_sel_hi:[1,0]
	s_waitcnt vmcnt(3)
	v_mov_b32_e32 v74, v98
	s_waitcnt vmcnt(2)
	v_mov_b32_e32 v75, v102
	s_waitcnt vmcnt(1)
	v_mov_b32_e32 v76, v106
	s_waitcnt vmcnt(0)
	v_mov_b32_e32 v77, v110
	v_pk_fma_f32 v[72:73], v[72:73], v[74:75], v[76:77]
	v_pk_mul_f32 v[74:75], v[134:135], v[0:1] op_sel_hi:[1,0]
	v_pk_mul_f32 v[76:77], v[136:137], v[0:1] op_sel_hi:[1,0]
	v_mov_b32_e32 v78, v100
	v_mov_b32_e32 v79, v104
	v_mov_b32_e32 v90, v108
	v_mov_b32_e32 v91, v112
	v_pk_mul_f32 v[0:1], v[114:115], v[0:1] op_sel_hi:[1,0]
	v_mov_b32_e32 v104, v101
	v_mov_b32_e32 v112, v109
	v_mov_b32_e32 v102, v99
	v_mov_b32_e32 v110, v107
	v_pk_fma_f32 v[76:77], v[76:77], v[78:79], v[90:91]
	v_pk_fma_f32 v[78:79], v[0:1], v[104:105], v[112:113]
	v_cvt_pk_bf16_f32 v0, v14, v20
	v_cvt_pk_bf16_f32 v1, v22, v70
	v_pk_fma_f32 v[74:75], v[74:75], v[102:103], v[110:111]
	global_store_dwordx2 v[80:81], v[0:1], off
	v_cvt_pk_bf16_f32 v0, v15, v21
	v_cvt_pk_bf16_f32 v1, v23, v71
	global_store_dwordx2 v[80:81], v[0:1], off offset:512
	v_cvt_pk_bf16_f32 v0, v72, v74
	v_cvt_pk_bf16_f32 v1, v76, v78
	global_store_dwordx2 v[80:81], v[0:1], off offset:1024
	v_cvt_pk_bf16_f32 v0, v73, v75
	v_cvt_pk_bf16_f32 v1, v77, v79
	global_store_dwordx2 v[80:81], v[0:1], off offset:1536
	v_mov_b32_e32 v0, 0
	v_mov_b32_e32 v1, 0
	v_swap_b32 v25, v54
	v_swap_b32 v17, v14
	v_swap_b32 v27, v56
	v_swap_b32 v5, v20
	v_swap_b32 v29, v58
	v_swap_b32 v19, v22
	v_swap_b32 v31, v60
	v_swap_b32 v3, v70
	v_swap_b32 v47, v62
	v_swap_b32 v7, v72
	v_swap_b32 v49, v64
	v_swap_b32 v9, v74
	v_swap_b32 v51, v66
	v_swap_b32 v13, v76
	v_swap_b32 v53, v68
	v_swap_b32 v11, v78
.LBB0_69:
	v_lshl_add_u64 v[80:81], v[42:43], 0, s[0:1]
	s_mov_b64 s[24:25], 0x2221000
	s_mov_b64 s[26:27], 0x2223000
	v_lshl_add_u64 v[90:91], v[80:81], 0, s[24:25]
	v_lshl_add_u64 v[92:93], v[80:81], 0, s[26:27]
	global_load_dwordx4 v[142:145], v[90:91], off offset:-4096
	global_load_dwordx4 v[146:149], v[90:91], off offset:-3072
	global_load_dwordx4 v[150:153], v[90:91], off offset:-2048
	global_load_dwordx4 v[154:157], v[90:91], off offset:-1024
	global_load_dwordx4 v[162:165], v[90:91], off
	global_load_dwordx4 v[166:169], v[90:91], off offset:1024
	global_load_dwordx4 v[170:173], v[90:91], off offset:2048
	global_load_dwordx4 v[174:177], v[90:91], off offset:3072
	global_load_dwordx4 v[178:181], v[92:93], off offset:-4096
	global_load_dwordx4 v[182:185], v[92:93], off offset:-3072
	global_load_dwordx4 v[186:189], v[92:93], off offset:-2048
	global_load_dwordx4 v[190:193], v[92:93], off offset:-1024
	global_load_dwordx4 v[196:199], v[92:93], off
	global_load_dwordx4 v[200:203], v[92:93], off offset:1024
	global_load_dwordx4 v[236:239], v[92:93], off offset:2048
	global_load_dwordx4 v[240:243], v[92:93], off offset:3072
	s_waitcnt vmcnt(14)
	v_pk_mul_f32 v[244:245], v[26:27], v[142:143] op_sel:[0,1] op_sel_hi:[1,1]
	v_pk_mul_f32 v[246:247], v[4:5], v[142:143] op_sel:[0,1] op_sel_hi:[1,1]
	v_pk_mul_f32 v[248:249], v[56:57], v[146:147] op_sel:[0,1] op_sel_hi:[1,1]
	v_pk_mul_f32 v[250:251], v[20:21], v[146:147] op_sel:[0,1] op_sel_hi:[1,1]
	v_pk_fma_f32 v[244:245], v[24:25], v[142:143], v[244:245] op_sel:[0,0,0] op_sel_hi:[1,0,1]
	v_pk_fma_f32 v[246:247], v[16:17], v[142:143], v[246:247] op_sel:[0,0,0] op_sel_hi:[1,0,1]
	v_pk_fma_f32 v[248:249], v[54:55], v[146:147], v[248:249] op_sel:[0,0,0] op_sel_hi:[1,0,1]
	v_pk_fma_f32 v[250:251], v[14:15], v[146:147], v[250:251] op_sel:[0,0,0] op_sel_hi:[1,0,1]
	v_pk_fma_f32 v[244:245], v[28:29], v[144:145], v[244:245] op_sel:[0,0,0] op_sel_hi:[1,0,1]
	v_pk_fma_f32 v[246:247], v[18:19], v[144:145], v[246:247] op_sel:[0,0,0] op_sel_hi:[1,0,1]
	v_pk_fma_f32 v[248:249], v[58:59], v[148:149], v[248:249] op_sel:[0,0,0] op_sel_hi:[1,0,1]
	v_pk_fma_f32 v[250:251], v[22:23], v[148:149], v[250:251] op_sel:[0,0,0] op_sel_hi:[1,0,1]
	v_pk_fma_f32 v[244:245], v[30:31], v[144:145], v[244:245] op_sel:[0,1,0] op_sel_hi:[1,1,1]
	v_pk_fma_f32 v[246:247], v[2:3], v[144:145], v[246:247] op_sel:[0,1,0] op_sel_hi:[1,1,1]
	v_pk_fma_f32 v[248:249], v[60:61], v[148:149], v[248:249] op_sel:[0,1,0] op_sel_hi:[1,1,1]
	v_pk_fma_f32 v[250:251], v[70:71], v[148:149], v[250:251] op_sel:[0,1,0] op_sel_hi:[1,1,1]
	v_pk_add_f32 v[252:253], v[244:245], 0
	v_pk_add_f32 v[158:159], v[246:247], 0
	v_pk_add_f32 v[252:253], v[252:253], v[248:249]
	v_pk_add_f32 v[158:159], v[158:159], v[250:251]
	s_waitcnt vmcnt(12)
; DEVI void phase_p7(const int TIDX, const int BIDX, const int GDIM, KAP KA, unsigned char* WSB, float* OUTB, int l, unsigned char* smem) {
;     ...
; #pragma unroll 4
;       for (int c = 0; c < 36; ++c) {
;         float4 wv[4];
; #pragma unroll
;         for (int j = 0; j < 4; ++j) wv[j] = *(const float4*)(WR + c * 1024 + j * 256 + lane * 4);
; #pragma unroll
;         for (int t = 0; t < 4; ++t) {
;           float s = 0.f;
; #pragma unroll
;           for (int j = 0; j < 4; ++j) s += v[t][j].x * wv[j].x + v[t][j].y * wv[j].y + v[t][j].z * wv[j].z + v[t][j].w * wv[j].w;
;           s = wave_sum(s);
;           if (lane == c) mine[t] = s;
	v_pk_mul_f32 v[244:245], v[48:49], v[150:151] op_sel:[0,1] op_sel_hi:[1,1]
	v_pk_mul_f32 v[246:247], v[8:9], v[150:151] op_sel:[0,1] op_sel_hi:[1,1]
	v_pk_mul_f32 v[248:249], v[64:65], v[154:155] op_sel:[0,1] op_sel_hi:[1,1]
	v_pk_mul_f32 v[250:251], v[74:75], v[154:155] op_sel:[0,1] op_sel_hi:[1,1]
	v_pk_fma_f32 v[244:245], v[46:47], v[150:151], v[244:245] op_sel:[0,0,0] op_sel_hi:[1,0,1]
	v_pk_fma_f32 v[246:247], v[6:7], v[150:151], v[246:247] op_sel:[0,0,0] op_sel_hi:[1,0,1]
	v_pk_fma_f32 v[248:249], v[62:63], v[154:155], v[248:249] op_sel:[0,0,0] op_sel_hi:[1,0,1]
	v_pk_fma_f32 v[250:251], v[72:73], v[154:155], v[250:251] op_sel:[0,0,0] op_sel_hi:[1,0,1]
	v_pk_fma_f32 v[244:245], v[50:51], v[152:153], v[244:245] op_sel:[0,0,0] op_sel_hi:[1,0,1]
	v_pk_fma_f32 v[246:247], v[12:13], v[152:153], v[246:247] op_sel:[0,0,0] op_sel_hi:[1,0,1]
	v_pk_fma_f32 v[248:249], v[66:67], v[156:157], v[248:249] op_sel:[0,0,0] op_sel_hi:[1,0,1]
	v_pk_fma_f32 v[250:251], v[76:77], v[156:157], v[250:251] op_sel:[0,0,0] op_sel_hi:[1,0,1]
	v_pk_fma_f32 v[244:245], v[52:53], v[152:153], v[244:245] op_sel:[0,1,0] op_sel_hi:[1,1,1]
	v_pk_fma_f32 v[246:247], v[10:11], v[152:153], v[246:247] op_sel:[0,1,0] op_sel_hi:[1,1,1]
	v_pk_fma_f32 v[248:249], v[68:69], v[156:157], v[248:249] op_sel:[0,1,0] op_sel_hi:[1,1,1]
	v_pk_fma_f32 v[250:251], v[78:79], v[156:157], v[250:251] op_sel:[0,1,0] op_sel_hi:[1,1,1]
	v_pk_add_f32 v[252:253], v[252:253], v[244:245]
	v_pk_add_f32 v[158:159], v[158:159], v[246:247]
	v_pk_add_f32 v[252:253], v[252:253], v[248:249]
	v_pk_add_f32 v[158:159], v[158:159], v[250:251]
	s_mov_b32 m0, s2
	s_nop 0
	v_add_f32_dpp v252, v252, v252 quad_perm:[1,0,3,2] row_mask:0xf bank_mask:0xf bound_ctrl:1
	v_add_f32_dpp v253, v253, v253 quad_perm:[1,0,3,2] row_mask:0xf bank_mask:0xf bound_ctrl:1
	v_add_f32_dpp v158, v158, v158 quad_perm:[1,0,3,2] row_mask:0xf bank_mask:0xf bound_ctrl:1
	v_add_f32_dpp v159, v159, v159 quad_perm:[1,0,3,2] row_mask:0xf bank_mask:0xf bound_ctrl:1
	v_add_f32_dpp v252, v252, v252 quad_perm:[2,3,0,1] row_mask:0xf bank_mask:0xf bound_ctrl:1
	v_add_f32_dpp v253, v253, v253 quad_perm:[2,3,0,1] row_mask:0xf bank_mask:0xf bound_ctrl:1
	v_add_f32_dpp v158, v158, v158 quad_perm:[2,3,0,1] row_mask:0xf bank_mask:0xf bound_ctrl:1
	v_add_f32_dpp v159, v159, v159 quad_perm:[2,3,0,1] row_mask:0xf bank_mask:0xf bound_ctrl:1
	v_add_f32_dpp v252, v252, v252 row_half_mirror row_mask:0xf bank_mask:0xf bound_ctrl:1
	v_add_f32_dpp v253, v253, v253 row_half_mirror row_mask:0xf bank_mask:0xf bound_ctrl:1
	v_add_f32_dpp v158, v158, v158 row_half_mirror row_mask:0xf bank_mask:0xf bound_ctrl:1
	v_add_f32_dpp v159, v159, v159 row_half_mirror row_mask:0xf bank_mask:0xf bound_ctrl:1
	v_add_f32_dpp v252, v252, v252 row_mirror row_mask:0xf bank_mask:0xf bound_ctrl:1
	v_add_f32_dpp v253, v253, v253 row_mirror row_mask:0xf bank_mask:0xf bound_ctrl:1
	v_add_f32_dpp v158, v158, v158 row_mirror row_mask:0xf bank_mask:0xf bound_ctrl:1
	v_add_f32_dpp v159, v159, v159 row_mirror row_mask:0xf bank_mask:0xf bound_ctrl:1
	v_mov_b32_e32 v94, v252
	s_waitcnt vmcnt(10)
	v_pk_mul_f32 v[244:245], v[26:27], v[162:163] op_sel:[0,1] op_sel_hi:[1,1]
	v_mov_b32_dpp v94, v253 row_shr:4 row_mask:0xf bank_mask:0x2
	v_pk_mul_f32 v[246:247], v[4:5], v[162:163] op_sel:[0,1] op_sel_hi:[1,1]
	v_pk_mul_f32 v[248:249], v[56:57], v[166:167] op_sel:[0,1] op_sel_hi:[1,1]
	v_mov_b32_dpp v94, v158 row_shr:8 row_mask:0xf bank_mask:0x4
	v_pk_mul_f32 v[250:251], v[20:21], v[166:167] op_sel:[0,1] op_sel_hi:[1,1]
	v_pk_fma_f32 v[244:245], v[24:25], v[162:163], v[244:245] op_sel:[0,0,0] op_sel_hi:[1,0,1]
	v_mov_b32_dpp v94, v159 row_shr:12 row_mask:0xf bank_mask:0x8
	v_mov_b32_e32 v95, v94
	v_pk_fma_f32 v[246:247], v[16:17], v[162:163], v[246:247] op_sel:[0,0,0] op_sel_hi:[1,0,1]
	v_pk_fma_f32 v[248:249], v[54:55], v[166:167], v[248:249] op_sel:[0,0,0] op_sel_hi:[1,0,1]
	v_permlane16_swap_b32_e32 v94, v95
	v_pk_fma_f32 v[250:251], v[14:15], v[166:167], v[250:251] op_sel:[0,0,0] op_sel_hi:[1,0,1]
	v_add_f32_e32 v96, v94, v95
	v_mov_b32_e32 v97, v96
	v_pk_fma_f32 v[244:245], v[28:29], v[164:165], v[244:245] op_sel:[0,0,0] op_sel_hi:[1,0,1]
	v_pk_fma_f32 v[246:247], v[18:19], v[164:165], v[246:247] op_sel:[0,0,0] op_sel_hi:[1,0,1]
	v_permlane32_swap_b32_e32 v96, v97
	v_pk_fma_f32 v[248:249], v[58:59], v[168:169], v[248:249] op_sel:[0,0,0] op_sel_hi:[1,0,1]
	v_add_f32_e32 v98, v96, v97
	v_pk_fma_f32 v[250:251], v[22:23], v[168:169], v[250:251] op_sel:[0,0,0] op_sel_hi:[1,0,1]
	v_readlane_b32 s24, v98, 0
	v_readlane_b32 s25, v98, 4
	v_readlane_b32 s26, v98, 8
	v_readlane_b32 s27, v98, 12
	v_writelane_b32 v82, s24, m0
	v_writelane_b32 v33, s25, m0
	v_writelane_b32 v0, s26, m0
	v_writelane_b32 v1, s27, m0
	v_pk_fma_f32 v[244:245], v[30:31], v[164:165], v[244:245] op_sel:[0,1,0] op_sel_hi:[1,1,1]
	v_pk_fma_f32 v[246:247], v[2:3], v[164:165], v[246:247] op_sel:[0,1,0] op_sel_hi:[1,1,1]
	v_pk_fma_f32 v[248:249], v[60:61], v[168:169], v[248:249] op_sel:[0,1,0] op_sel_hi:[1,1,1]
	v_pk_fma_f32 v[250:251], v[70:71], v[168:169], v[250:251] op_sel:[0,1,0] op_sel_hi:[1,1,1]
	v_pk_add_f32 v[252:253], v[244:245], 0
	v_pk_add_f32 v[158:159], v[246:247], 0
	v_pk_add_f32 v[252:253], v[252:253], v[248:249]
	v_pk_add_f32 v[158:159], v[158:159], v[250:251]
	s_waitcnt vmcnt(8)
; DEVI void phase_p7(const int TIDX, const int BIDX, const int GDIM, KAP KA, unsigned char* WSB, float* OUTB, int l, unsigned char* smem) {
;     ...
; #pragma unroll 4
;       for (int c = 0; c < 36; ++c) {
;         float4 wv[4];
; #pragma unroll
;         for (int j = 0; j < 4; ++j) wv[j] = *(const float4*)(WR + c * 1024 + j * 256 + lane * 4);
; #pragma unroll
;         for (int t = 0; t < 4; ++t) {
;           float s = 0.f;
; #pragma unroll
;           for (int j = 0; j < 4; ++j) s += v[t][j].x * wv[j].x + v[t][j].y * wv[j].y + v[t][j].z * wv[j].z + v[t][j].w * wv[j].w;
;           s = wave_sum(s);
;           if (lane == c) mine[t] = s;
	v_pk_mul_f32 v[244:245], v[48:49], v[170:171] op_sel:[0,1] op_sel_hi:[1,1]
	v_pk_mul_f32 v[246:247], v[8:9], v[170:171] op_sel:[0,1] op_sel_hi:[1,1]
	v_pk_mul_f32 v[248:249], v[64:65], v[174:175] op_sel:[0,1] op_sel_hi:[1,1]
	v_pk_mul_f32 v[250:251], v[74:75], v[174:175] op_sel:[0,1] op_sel_hi:[1,1]
	v_pk_fma_f32 v[244:245], v[46:47], v[170:171], v[244:245] op_sel:[0,0,0] op_sel_hi:[1,0,1]
	v_pk_fma_f32 v[246:247], v[6:7], v[170:171], v[246:247] op_sel:[0,0,0] op_sel_hi:[1,0,1]
	v_pk_fma_f32 v[248:249], v[62:63], v[174:175], v[248:249] op_sel:[0,0,0] op_sel_hi:[1,0,1]
	v_pk_fma_f32 v[250:251], v[72:73], v[174:175], v[250:251] op_sel:[0,0,0] op_sel_hi:[1,0,1]
	v_pk_fma_f32 v[244:245], v[50:51], v[172:173], v[244:245] op_sel:[0,0,0] op_sel_hi:[1,0,1]
	v_pk_fma_f32 v[246:247], v[12:13], v[172:173], v[246:247] op_sel:[0,0,0] op_sel_hi:[1,0,1]
	v_pk_fma_f32 v[248:249], v[66:67], v[176:177], v[248:249] op_sel:[0,0,0] op_sel_hi:[1,0,1]
	v_pk_fma_f32 v[250:251], v[76:77], v[176:177], v[250:251] op_sel:[0,0,0] op_sel_hi:[1,0,1]
	v_pk_fma_f32 v[244:245], v[52:53], v[172:173], v[244:245] op_sel:[0,1,0] op_sel_hi:[1,1,1]
	v_pk_fma_f32 v[246:247], v[10:11], v[172:173], v[246:247] op_sel:[0,1,0] op_sel_hi:[1,1,1]
	v_pk_fma_f32 v[248:249], v[68:69], v[176:177], v[248:249] op_sel:[0,1,0] op_sel_hi:[1,1,1]
	v_pk_fma_f32 v[250:251], v[78:79], v[176:177], v[250:251] op_sel:[0,1,0] op_sel_hi:[1,1,1]
	v_pk_add_f32 v[252:253], v[252:253], v[244:245]
	v_pk_add_f32 v[158:159], v[158:159], v[246:247]
	v_pk_add_f32 v[252:253], v[252:253], v[248:249]
	v_pk_add_f32 v[158:159], v[158:159], v[250:251]
	s_or_b32 s101, s2, 1
	s_mov_b32 m0, s101
	v_add_f32_dpp v252, v252, v252 quad_perm:[1,0,3,2] row_mask:0xf bank_mask:0xf bound_ctrl:1
	v_add_f32_dpp v253, v253, v253 quad_perm:[1,0,3,2] row_mask:0xf bank_mask:0xf bound_ctrl:1
	v_add_f32_dpp v158, v158, v158 quad_perm:[1,0,3,2] row_mask:0xf bank_mask:0xf bound_ctrl:1
	v_add_f32_dpp v159, v159, v159 quad_perm:[1,0,3,2] row_mask:0xf bank_mask:0xf bound_ctrl:1
	v_add_f32_dpp v252, v252, v252 quad_perm:[2,3,0,1] row_mask:0xf bank_mask:0xf bound_ctrl:1
	v_add_f32_dpp v253, v253, v253 quad_perm:[2,3,0,1] row_mask:0xf bank_mask:0xf bound_ctrl:1
	v_add_f32_dpp v158, v158, v158 quad_perm:[2,3,0,1] row_mask:0xf bank_mask:0xf bound_ctrl:1
	v_add_f32_dpp v159, v159, v159 quad_perm:[2,3,0,1] row_mask:0xf bank_mask:0xf bound_ctrl:1
	v_add_f32_dpp v252, v252, v252 row_half_mirror row_mask:0xf bank_mask:0xf bound_ctrl:1
	v_add_f32_dpp v253, v253, v253 row_half_mirror row_mask:0xf bank_mask:0xf bound_ctrl:1
	v_add_f32_dpp v158, v158, v158 row_half_mirror row_mask:0xf bank_mask:0xf bound_ctrl:1
	v_add_f32_dpp v159, v159, v159 row_half_mirror row_mask:0xf bank_mask:0xf bound_ctrl:1
	v_add_f32_dpp v252, v252, v252 row_mirror row_mask:0xf bank_mask:0xf bound_ctrl:1
	v_add_f32_dpp v253, v253, v253 row_mirror row_mask:0xf bank_mask:0xf bound_ctrl:1
	v_add_f32_dpp v158, v158, v158 row_mirror row_mask:0xf bank_mask:0xf bound_ctrl:1
	v_add_f32_dpp v159, v159, v159 row_mirror row_mask:0xf bank_mask:0xf bound_ctrl:1
	v_mov_b32_e32 v94, v252
	s_waitcnt vmcnt(6)
	v_pk_mul_f32 v[244:245], v[26:27], v[178:179] op_sel:[0,1] op_sel_hi:[1,1]
	v_mov_b32_dpp v94, v253 row_shr:4 row_mask:0xf bank_mask:0x2
	v_pk_mul_f32 v[246:247], v[4:5], v[178:179] op_sel:[0,1] op_sel_hi:[1,1]
	v_pk_mul_f32 v[248:249], v[56:57], v[182:183] op_sel:[0,1] op_sel_hi:[1,1]
	v_mov_b32_dpp v94, v158 row_shr:8 row_mask:0xf bank_mask:0x4
	v_pk_mul_f32 v[250:251], v[20:21], v[182:183] op_sel:[0,1] op_sel_hi:[1,1]
	v_pk_fma_f32 v[244:245], v[24:25], v[178:179], v[244:245] op_sel:[0,0,0] op_sel_hi:[1,0,1]
	v_mov_b32_dpp v94, v159 row_shr:12 row_mask:0xf bank_mask:0x8
	v_mov_b32_e32 v95, v94
	v_pk_fma_f32 v[246:247], v[16:17], v[178:179], v[246:247] op_sel:[0,0,0] op_sel_hi:[1,0,1]
	v_pk_fma_f32 v[248:249], v[54:55], v[182:183], v[248:249] op_sel:[0,0,0] op_sel_hi:[1,0,1]
	v_permlane16_swap_b32_e32 v94, v95
	v_pk_fma_f32 v[250:251], v[14:15], v[182:183], v[250:251] op_sel:[0,0,0] op_sel_hi:[1,0,1]
	v_add_f32_e32 v96, v94, v95
	v_mov_b32_e32 v97, v96
	v_pk_fma_f32 v[244:245], v[28:29], v[180:181], v[244:245] op_sel:[0,0,0] op_sel_hi:[1,0,1]
	v_pk_fma_f32 v[246:247], v[18:19], v[180:181], v[246:247] op_sel:[0,0,0] op_sel_hi:[1,0,1]
	v_permlane32_swap_b32_e32 v96, v97
	v_pk_fma_f32 v[248:249], v[58:59], v[184:185], v[248:249] op_sel:[0,0,0] op_sel_hi:[1,0,1]
	v_add_f32_e32 v98, v96, v97
	v_pk_fma_f32 v[250:251], v[22:23], v[184:185], v[250:251] op_sel:[0,0,0] op_sel_hi:[1,0,1]
	v_readlane_b32 s24, v98, 0
	v_readlane_b32 s25, v98, 4
	v_readlane_b32 s26, v98, 8
	v_readlane_b32 s27, v98, 12
	v_writelane_b32 v82, s24, m0
	v_writelane_b32 v33, s25, m0
	v_writelane_b32 v0, s26, m0
	v_writelane_b32 v1, s27, m0
	v_pk_fma_f32 v[244:245], v[30:31], v[180:181], v[244:245] op_sel:[0,1,0] op_sel_hi:[1,1,1]
	v_pk_fma_f32 v[246:247], v[2:3], v[180:181], v[246:247] op_sel:[0,1,0] op_sel_hi:[1,1,1]
	v_pk_fma_f32 v[248:249], v[60:61], v[184:185], v[248:249] op_sel:[0,1,0] op_sel_hi:[1,1,1]
	v_pk_fma_f32 v[250:251], v[70:71], v[184:185], v[250:251] op_sel:[0,1,0] op_sel_hi:[1,1,1]
	v_pk_add_f32 v[252:253], v[244:245], 0
	v_pk_add_f32 v[158:159], v[246:247], 0
	v_pk_add_f32 v[252:253], v[252:253], v[248:249]
	v_pk_add_f32 v[158:159], v[158:159], v[250:251]
	s_waitcnt vmcnt(4)
; DEVI void phase_p7(const int TIDX, const int BIDX, const int GDIM, KAP KA, unsigned char* WSB, float* OUTB, int l, unsigned char* smem) {
;     ...
; #pragma unroll 4
;       for (int c = 0; c < 36; ++c) {
;         float4 wv[4];
; #pragma unroll
;         for (int j = 0; j < 4; ++j) wv[j] = *(const float4*)(WR + c * 1024 + j * 256 + lane * 4);
; #pragma unroll
;         for (int t = 0; t < 4; ++t) {
;           float s = 0.f;
; #pragma unroll
;           for (int j = 0; j < 4; ++j) s += v[t][j].x * wv[j].x + v[t][j].y * wv[j].y + v[t][j].z * wv[j].z + v[t][j].w * wv[j].w;
;           s = wave_sum(s);
;           if (lane == c) mine[t] = s;
	v_pk_mul_f32 v[244:245], v[48:49], v[186:187] op_sel:[0,1] op_sel_hi:[1,1]
	v_pk_mul_f32 v[246:247], v[8:9], v[186:187] op_sel:[0,1] op_sel_hi:[1,1]
	v_pk_mul_f32 v[248:249], v[64:65], v[190:191] op_sel:[0,1] op_sel_hi:[1,1]
	v_pk_mul_f32 v[250:251], v[74:75], v[190:191] op_sel:[0,1] op_sel_hi:[1,1]
	v_pk_fma_f32 v[244:245], v[46:47], v[186:187], v[244:245] op_sel:[0,0,0] op_sel_hi:[1,0,1]
	v_pk_fma_f32 v[246:247], v[6:7], v[186:187], v[246:247] op_sel:[0,0,0] op_sel_hi:[1,0,1]
	v_pk_fma_f32 v[248:249], v[62:63], v[190:191], v[248:249] op_sel:[0,0,0] op_sel_hi:[1,0,1]
	v_pk_fma_f32 v[250:251], v[72:73], v[190:191], v[250:251] op_sel:[0,0,0] op_sel_hi:[1,0,1]
	v_pk_fma_f32 v[244:245], v[50:51], v[188:189], v[244:245] op_sel:[0,0,0] op_sel_hi:[1,0,1]
	v_pk_fma_f32 v[246:247], v[12:13], v[188:189], v[246:247] op_sel:[0,0,0] op_sel_hi:[1,0,1]
	v_pk_fma_f32 v[248:249], v[66:67], v[192:193], v[248:249] op_sel:[0,0,0] op_sel_hi:[1,0,1]
	v_pk_fma_f32 v[250:251], v[76:77], v[192:193], v[250:251] op_sel:[0,0,0] op_sel_hi:[1,0,1]
	v_pk_fma_f32 v[244:245], v[52:53], v[188:189], v[244:245] op_sel:[0,1,0] op_sel_hi:[1,1,1]
	v_pk_fma_f32 v[246:247], v[10:11], v[188:189], v[246:247] op_sel:[0,1,0] op_sel_hi:[1,1,1]
	v_pk_fma_f32 v[248:249], v[68:69], v[192:193], v[248:249] op_sel:[0,1,0] op_sel_hi:[1,1,1]
	v_pk_fma_f32 v[250:251], v[78:79], v[192:193], v[250:251] op_sel:[0,1,0] op_sel_hi:[1,1,1]
	v_pk_add_f32 v[252:253], v[252:253], v[244:245]
	v_pk_add_f32 v[158:159], v[158:159], v[246:247]
	v_pk_add_f32 v[252:253], v[252:253], v[248:249]
	v_pk_add_f32 v[158:159], v[158:159], v[250:251]
	s_or_b32 s101, s2, 2
	s_mov_b32 m0, s101
	v_add_f32_dpp v252, v252, v252 quad_perm:[1,0,3,2] row_mask:0xf bank_mask:0xf bound_ctrl:1
	v_add_f32_dpp v253, v253, v253 quad_perm:[1,0,3,2] row_mask:0xf bank_mask:0xf bound_ctrl:1
	v_add_f32_dpp v158, v158, v158 quad_perm:[1,0,3,2] row_mask:0xf bank_mask:0xf bound_ctrl:1
	v_add_f32_dpp v159, v159, v159 quad_perm:[1,0,3,2] row_mask:0xf bank_mask:0xf bound_ctrl:1
	v_add_f32_dpp v252, v252, v252 quad_perm:[2,3,0,1] row_mask:0xf bank_mask:0xf bound_ctrl:1
	v_add_f32_dpp v253, v253, v253 quad_perm:[2,3,0,1] row_mask:0xf bank_mask:0xf bound_ctrl:1
	v_add_f32_dpp v158, v158, v158 quad_perm:[2,3,0,1] row_mask:0xf bank_mask:0xf bound_ctrl:1
	v_add_f32_dpp v159, v159, v159 quad_perm:[2,3,0,1] row_mask:0xf bank_mask:0xf bound_ctrl:1
	v_add_f32_dpp v252, v252, v252 row_half_mirror row_mask:0xf bank_mask:0xf bound_ctrl:1
	v_add_f32_dpp v253, v253, v253 row_half_mirror row_mask:0xf bank_mask:0xf bound_ctrl:1
	v_add_f32_dpp v158, v158, v158 row_half_mirror row_mask:0xf bank_mask:0xf bound_ctrl:1
	v_add_f32_dpp v159, v159, v159 row_half_mirror row_mask:0xf bank_mask:0xf bound_ctrl:1
	v_add_f32_dpp v252, v252, v252 row_mirror row_mask:0xf bank_mask:0xf bound_ctrl:1
	v_add_f32_dpp v253, v253, v253 row_mirror row_mask:0xf bank_mask:0xf bound_ctrl:1
	v_add_f32_dpp v158, v158, v158 row_mirror row_mask:0xf bank_mask:0xf bound_ctrl:1
	v_add_f32_dpp v159, v159, v159 row_mirror row_mask:0xf bank_mask:0xf bound_ctrl:1
	v_mov_b32_e32 v94, v252
	s_waitcnt vmcnt(2)
	v_pk_mul_f32 v[244:245], v[26:27], v[196:197] op_sel:[0,1] op_sel_hi:[1,1]
	v_mov_b32_dpp v94, v253 row_shr:4 row_mask:0xf bank_mask:0x2
	v_pk_mul_f32 v[246:247], v[4:5], v[196:197] op_sel:[0,1] op_sel_hi:[1,1]
	v_pk_mul_f32 v[248:249], v[56:57], v[200:201] op_sel:[0,1] op_sel_hi:[1,1]
	v_mov_b32_dpp v94, v158 row_shr:8 row_mask:0xf bank_mask:0x4
	v_pk_mul_f32 v[250:251], v[20:21], v[200:201] op_sel:[0,1] op_sel_hi:[1,1]
	v_pk_fma_f32 v[244:245], v[24:25], v[196:197], v[244:245] op_sel:[0,0,0] op_sel_hi:[1,0,1]
	v_mov_b32_dpp v94, v159 row_shr:12 row_mask:0xf bank_mask:0x8
	v_mov_b32_e32 v95, v94
	v_pk_fma_f32 v[246:247], v[16:17], v[196:197], v[246:247] op_sel:[0,0,0] op_sel_hi:[1,0,1]
	v_pk_fma_f32 v[248:249], v[54:55], v[200:201], v[248:249] op_sel:[0,0,0] op_sel_hi:[1,0,1]
	v_permlane16_swap_b32_e32 v94, v95
	v_pk_fma_f32 v[250:251], v[14:15], v[200:201], v[250:251] op_sel:[0,0,0] op_sel_hi:[1,0,1]
	v_add_f32_e32 v96, v94, v95
	v_mov_b32_e32 v97, v96
	v_pk_fma_f32 v[244:245], v[28:29], v[198:199], v[244:245] op_sel:[0,0,0] op_sel_hi:[1,0,1]
	v_pk_fma_f32 v[246:247], v[18:19], v[198:199], v[246:247] op_sel:[0,0,0] op_sel_hi:[1,0,1]
	v_permlane32_swap_b32_e32 v96, v97
	v_pk_fma_f32 v[248:249], v[58:59], v[202:203], v[248:249] op_sel:[0,0,0] op_sel_hi:[1,0,1]
	v_add_f32_e32 v98, v96, v97
	v_pk_fma_f32 v[250:251], v[22:23], v[202:203], v[250:251] op_sel:[0,0,0] op_sel_hi:[1,0,1]
	v_readlane_b32 s24, v98, 0
	v_readlane_b32 s25, v98, 4
	v_readlane_b32 s26, v98, 8
	v_readlane_b32 s27, v98, 12
	v_writelane_b32 v82, s24, m0
	v_writelane_b32 v33, s25, m0
	v_writelane_b32 v0, s26, m0
	v_writelane_b32 v1, s27, m0
	v_pk_fma_f32 v[244:245], v[30:31], v[198:199], v[244:245] op_sel:[0,1,0] op_sel_hi:[1,1,1]
	v_pk_fma_f32 v[246:247], v[2:3], v[198:199], v[246:247] op_sel:[0,1,0] op_sel_hi:[1,1,1]
	v_pk_fma_f32 v[248:249], v[60:61], v[202:203], v[248:249] op_sel:[0,1,0] op_sel_hi:[1,1,1]
	v_pk_fma_f32 v[250:251], v[70:71], v[202:203], v[250:251] op_sel:[0,1,0] op_sel_hi:[1,1,1]
	v_pk_add_f32 v[252:253], v[244:245], 0
	v_pk_add_f32 v[158:159], v[246:247], 0
	v_pk_add_f32 v[252:253], v[252:253], v[248:249]
	v_pk_add_f32 v[158:159], v[158:159], v[250:251]
	s_waitcnt vmcnt(0)
; DEVI void phase_p7(const int TIDX, const int BIDX, const int GDIM, KAP KA, unsigned char* WSB, float* OUTB, int l, unsigned char* smem) {
;     ...
; #pragma unroll 4
;       for (int c = 0; c < 36; ++c) {
;         float4 wv[4];
; #pragma unroll
;         for (int j = 0; j < 4; ++j) wv[j] = *(const float4*)(WR + c * 1024 + j * 256 + lane * 4);
; #pragma unroll
;         for (int t = 0; t < 4; ++t) {
;           float s = 0.f;
; #pragma unroll
;           for (int j = 0; j < 4; ++j) s += v[t][j].x * wv[j].x + v[t][j].y * wv[j].y + v[t][j].z * wv[j].z + v[t][j].w * wv[j].w;
;           s = wave_sum(s);
;           if (lane == c) mine[t] = s;
;         }
;       }
;       int my_e = 0, my_tk = 0; float my_w = 0.f;
; #pragma unroll
;       for (int t = 0; t < 4; ++t) {
;         const int tok = r4 * 4 + t;
;         float gl[4];
; #pragma unroll
;         for (int j = 0; j < 4; ++j) gl[j] = __shfl(mine[t], j);
;         int gi = 0; float gm = gl[0];
; #pragma unroll
;         for (int j = 1; j < 4; ++j) if (gl[j] > gm) { gm = gl[j]; gi = j; }
	v_pk_mul_f32 v[244:245], v[48:49], v[236:237] op_sel:[0,1] op_sel_hi:[1,1]
	v_pk_mul_f32 v[246:247], v[8:9], v[236:237] op_sel:[0,1] op_sel_hi:[1,1]
	v_pk_mul_f32 v[248:249], v[64:65], v[240:241] op_sel:[0,1] op_sel_hi:[1,1]
	v_pk_mul_f32 v[250:251], v[74:75], v[240:241] op_sel:[0,1] op_sel_hi:[1,1]
	v_pk_fma_f32 v[244:245], v[46:47], v[236:237], v[244:245] op_sel:[0,0,0] op_sel_hi:[1,0,1]
	v_pk_fma_f32 v[246:247], v[6:7], v[236:237], v[246:247] op_sel:[0,0,0] op_sel_hi:[1,0,1]
	v_pk_fma_f32 v[248:249], v[62:63], v[240:241], v[248:249] op_sel:[0,0,0] op_sel_hi:[1,0,1]
	v_pk_fma_f32 v[250:251], v[72:73], v[240:241], v[250:251] op_sel:[0,0,0] op_sel_hi:[1,0,1]
	v_pk_fma_f32 v[244:245], v[50:51], v[238:239], v[244:245] op_sel:[0,0,0] op_sel_hi:[1,0,1]
	v_pk_fma_f32 v[246:247], v[12:13], v[238:239], v[246:247] op_sel:[0,0,0] op_sel_hi:[1,0,1]
	v_pk_fma_f32 v[248:249], v[66:67], v[242:243], v[248:249] op_sel:[0,0,0] op_sel_hi:[1,0,1]
	v_pk_fma_f32 v[250:251], v[76:77], v[242:243], v[250:251] op_sel:[0,0,0] op_sel_hi:[1,0,1]
	v_pk_fma_f32 v[244:245], v[52:53], v[238:239], v[244:245] op_sel:[0,1,0] op_sel_hi:[1,1,1]
	v_pk_fma_f32 v[246:247], v[10:11], v[238:239], v[246:247] op_sel:[0,1,0] op_sel_hi:[1,1,1]
	v_pk_fma_f32 v[248:249], v[68:69], v[242:243], v[248:249] op_sel:[0,1,0] op_sel_hi:[1,1,1]
	v_pk_fma_f32 v[250:251], v[78:79], v[242:243], v[250:251] op_sel:[0,1,0] op_sel_hi:[1,1,1]
	v_pk_add_f32 v[252:253], v[252:253], v[244:245]
	v_pk_add_f32 v[158:159], v[158:159], v[246:247]
	v_pk_add_f32 v[252:253], v[252:253], v[248:249]
	v_pk_add_f32 v[158:159], v[158:159], v[250:251]
	s_or_b32 s101, s2, 3
	s_mov_b32 m0, s101
	v_add_f32_dpp v252, v252, v252 quad_perm:[1,0,3,2] row_mask:0xf bank_mask:0xf bound_ctrl:1
	v_add_f32_dpp v253, v253, v253 quad_perm:[1,0,3,2] row_mask:0xf bank_mask:0xf bound_ctrl:1
	v_add_f32_dpp v158, v158, v158 quad_perm:[1,0,3,2] row_mask:0xf bank_mask:0xf bound_ctrl:1
	v_add_f32_dpp v159, v159, v159 quad_perm:[1,0,3,2] row_mask:0xf bank_mask:0xf bound_ctrl:1
	v_add_f32_dpp v252, v252, v252 quad_perm:[2,3,0,1] row_mask:0xf bank_mask:0xf bound_ctrl:1
	v_add_f32_dpp v253, v253, v253 quad_perm:[2,3,0,1] row_mask:0xf bank_mask:0xf bound_ctrl:1
	v_add_f32_dpp v158, v158, v158 quad_perm:[2,3,0,1] row_mask:0xf bank_mask:0xf bound_ctrl:1
	v_add_f32_dpp v159, v159, v159 quad_perm:[2,3,0,1] row_mask:0xf bank_mask:0xf bound_ctrl:1
	v_add_f32_dpp v252, v252, v252 row_half_mirror row_mask:0xf bank_mask:0xf bound_ctrl:1
	v_add_f32_dpp v253, v253, v253 row_half_mirror row_mask:0xf bank_mask:0xf bound_ctrl:1
	v_add_f32_dpp v158, v158, v158 row_half_mirror row_mask:0xf bank_mask:0xf bound_ctrl:1
	v_add_f32_dpp v159, v159, v159 row_half_mirror row_mask:0xf bank_mask:0xf bound_ctrl:1
	v_add_f32_dpp v252, v252, v252 row_mirror row_mask:0xf bank_mask:0xf bound_ctrl:1
	v_add_f32_dpp v253, v253, v253 row_mirror row_mask:0xf bank_mask:0xf bound_ctrl:1
	v_add_f32_dpp v158, v158, v158 row_mirror row_mask:0xf bank_mask:0xf bound_ctrl:1
	v_add_f32_dpp v159, v159, v159 row_mirror row_mask:0xf bank_mask:0xf bound_ctrl:1
	v_mov_b32_e32 v94, v252
	s_add_i32 s2, s2, 4
	s_add_u32 s0, s0, 0x4000
	v_mov_b32_dpp v94, v253 row_shr:4 row_mask:0xf bank_mask:0x2
	s_addc_u32 s1, s1, 0
	s_nop 0
	v_mov_b32_dpp v94, v158 row_shr:8 row_mask:0xf bank_mask:0x4
	s_nop 0
	s_nop 0
	v_mov_b32_dpp v94, v159 row_shr:12 row_mask:0xf bank_mask:0x8
	v_mov_b32_e32 v95, v94
	s_nop 0
	s_nop 0
	v_permlane16_swap_b32_e32 v94, v95
	s_nop 0
	v_add_f32_e32 v96, v94, v95
	v_mov_b32_e32 v97, v96
	s_nop 0
	s_nop 0
	v_permlane32_swap_b32_e32 v96, v97
	s_nop 0
	v_add_f32_e32 v98, v96, v97
	s_nop 0
	v_readlane_b32 s24, v98, 0
	v_readlane_b32 s25, v98, 4
	v_readlane_b32 s26, v98, 8
	v_readlane_b32 s27, v98, 12
	v_writelane_b32 v82, s24, m0
	v_writelane_b32 v33, s25, m0
	v_writelane_b32 v0, s26, m0
	v_writelane_b32 v1, s27, m0
	s_cmp_eq_u32 s2, 36
	s_cbranch_scc0 .LBB0_69
	v_bfe_u32 v154, v45, 1, 2
	ds_bpermute_b32 v2, v85, v82
	ds_bpermute_b32 v3, v86, v82
	ds_bpermute_b32 v4, v87, v82
	ds_bpermute_b32 v5, v88, v82
	ds_bpermute_b32 v142, v85, v33
	ds_bpermute_b32 v143, v86, v33
	ds_bpermute_b32 v144, v87, v33
	ds_bpermute_b32 v145, v88, v33
	ds_bpermute_b32 v146, v85, v0
	ds_bpermute_b32 v147, v86, v0
	ds_bpermute_b32 v148, v87, v0
	ds_bpermute_b32 v149, v88, v0
	ds_bpermute_b32 v150, v85, v1
	ds_bpermute_b32 v151, v86, v1
	ds_bpermute_b32 v152, v87, v1
	ds_bpermute_b32 v153, v88, v1
	s_waitcnt lgkmcnt(0)
	v_cmp_eq_u32_e32 vcc, 1, v154
	s_nop 1
	v_cndmask_b32_e32 v2, v2, v142, vcc
	v_cndmask_b32_e32 v3, v3, v143, vcc
	v_cndmask_b32_e32 v4, v4, v144, vcc
	v_cndmask_b32_e32 v5, v5, v145, vcc
	v_cmp_eq_u32_e32 vcc, 2, v154
	s_nop 1
	v_cndmask_b32_e32 v2, v2, v146, vcc
	v_cndmask_b32_e32 v3, v3, v147, vcc
	v_cndmask_b32_e32 v4, v4, v148, vcc
	v_cndmask_b32_e32 v5, v5, v149, vcc
	v_cmp_eq_u32_e32 vcc, 3, v154
	s_nop 1
	v_cndmask_b32_e32 v2, v2, v150, vcc
	v_cndmask_b32_e32 v3, v3, v151, vcc
	v_cndmask_b32_e32 v4, v4, v152, vcc
	v_cndmask_b32_e32 v5, v5, v153, vcc
	s_waitcnt lgkmcnt(2)
	v_cmp_gt_f32_e32 vcc, v3, v2
	s_nop 1
	v_cndmask_b32_e32 v6, v2, v3, vcc
	s_waitcnt lgkmcnt(1)
	v_cmp_lt_f32_e64 s[22:23], v6, v4
	s_nop 1
	v_cndmask_b32_e64 v6, v6, v4, s[22:23]
	s_waitcnt lgkmcnt(0)
; DEVI void phase_p7(const int TIDX, const int BIDX, const int GDIM, KAP KA, unsigned char* WSB, float* OUTB, int l, unsigned char* smem) {
;     ...
;         for (int j = 0; j < 4; ++j) gl[j] = __shfl(mine[t], j);
;         int gi = 0; float gm = gl[0];
; #pragma unroll
;         for (int j = 1; j < 4; ++j) if (gl[j] > gm) { gm = gl[j]; gi = j; }
;         float gs = 0.f;
; #pragma unroll
;         for (int j = 0; j < 4; ++j) gs += expf(gl[j] - gm);
;         const float gtop = 1.f / gs;
;         float el[8];
; #pragma unroll
;         for (int j = 0; j < 8; ++j) el[j] = __shfl(mine[t], 4 + gi * 8 + j);
;         float em = el[0];
; #pragma unroll
;         for (int j = 1; j < 8; ++j) em = fmaxf(em, el[j]);
	v_cmp_lt_f32_e64 s[24:25], v6, v5
	s_nop 1
	v_cndmask_b32_e64 v6, v6, v5, s[24:25]
	v_sub_f32_e32 v7, v2, v6
	v_sub_f32_e32 v2, v3, v6
	v_mul_f32_e32 v3, 0x3fb8aa3b, v2
	v_fma_f32 v8, v2, s61, -v3
	v_rndne_f32_e32 v9, v3
	v_fmac_f32_e32 v8, 0x32a5705f, v2
	v_sub_f32_e32 v3, v3, v9
	v_add_f32_e32 v3, v3, v8
	v_exp_f32_e32 v3, v3
	v_cvt_i32_f32_e32 v8, v9
	v_cmp_ngt_f32_e64 s[26:27], s90, v2
	v_mul_f32_e32 v16, 0x3fb8aa3b, v7
	v_fma_f32 v17, v7, s61, -v16
	v_ldexp_f32 v3, v3, v8
	v_cndmask_b32_e64 v3, 0, v3, s[26:27]
	v_cmp_nlt_f32_e64 s[26:27], s91, v2
	v_sub_f32_e32 v2, v4, v6
	v_mul_f32_e32 v4, 0x3fb8aa3b, v2
	v_fma_f32 v8, v2, s61, -v4
	v_rndne_f32_e32 v9, v4
	v_fmac_f32_e32 v8, 0x32a5705f, v2
	v_sub_f32_e32 v4, v4, v9
	v_add_f32_e32 v4, v4, v8
	v_exp_f32_e32 v4, v4
	v_cvt_i32_f32_e32 v8, v9
	v_cndmask_b32_e64 v3, v229, v3, s[26:27]
	v_cmp_ngt_f32_e64 s[26:27], s90, v2
	v_rndne_f32_e32 v18, v16
	v_ldexp_f32 v4, v4, v8
	v_cndmask_b32_e64 v4, 0, v4, s[26:27]
	v_cmp_nlt_f32_e64 s[26:27], s91, v2
	v_sub_f32_e32 v2, v5, v6
	v_mul_f32_e32 v5, 0x3fb8aa3b, v2
	v_fma_f32 v6, v2, s61, -v5
	v_rndne_f32_e32 v8, v5
	v_fmac_f32_e32 v6, 0x32a5705f, v2
	v_sub_f32_e32 v5, v5, v8
	v_add_f32_e32 v5, v5, v6
	v_exp_f32_e32 v5, v5
	v_cvt_i32_f32_e32 v6, v8
	v_cndmask_b32_e64 v4, v229, v4, s[26:27]
	v_cmp_ngt_f32_e64 s[26:27], s90, v2
	v_fmac_f32_e32 v17, 0x32a5705f, v7
	v_ldexp_f32 v5, v5, v6
	v_cndmask_b32_e64 v5, 0, v5, s[26:27]
	v_cmp_nlt_f32_e64 s[26:27], s91, v2
	v_sub_f32_e32 v16, v16, v18
	v_add_f32_e32 v16, v16, v17
	v_cndmask_b32_e64 v6, v229, v5, s[26:27]
	v_cndmask_b32_e64 v5, 0, 8, vcc
	v_cndmask_b32_e64 v5, v5, 16, s[22:23]
	v_exp_f32_e32 v16, v16
	v_cvt_i32_f32_e32 v17, v18
	v_cndmask_b32_e64 v5, v5, 24, s[24:25]
	v_or_b32_e32 v8, v5, v84
	v_lshlrev_b32_e32 v8, 2, v8
	v_mov_b32_e32 v155, v8
	ds_bpermute_b32 v9, v8, v82
	ds_bpermute_b32 v10, v8, v82 offset:4
	v_ldexp_f32 v16, v16, v17
	v_cmp_ngt_f32_e32 vcc, s90, v7
	ds_bpermute_b32 v11, v8, v82 offset:8
	ds_bpermute_b32 v12, v8, v82 offset:12
	v_cndmask_b32_e32 v16, 0, v16, vcc
	v_cmp_nlt_f32_e32 vcc, s91, v7
	ds_bpermute_b32 v13, v8, v82 offset:16
	ds_bpermute_b32 v14, v8, v82 offset:20
	v_cndmask_b32_e32 v7, v229, v16, vcc
	v_add_f32_e32 v3, v7, v3
	ds_bpermute_b32 v15, v8, v82 offset:24
	ds_bpermute_b32 v8, v8, v82 offset:28
	ds_bpermute_b32 v156, v155, v33
	ds_bpermute_b32 v157, v155, v33 offset:4
	ds_bpermute_b32 v158, v155, v33 offset:8
	ds_bpermute_b32 v159, v155, v33 offset:12
	ds_bpermute_b32 v160, v155, v33 offset:16
	ds_bpermute_b32 v162, v155, v33 offset:20
	ds_bpermute_b32 v163, v155, v33 offset:24
	ds_bpermute_b32 v164, v155, v33 offset:28
	ds_bpermute_b32 v165, v155, v0
	ds_bpermute_b32 v166, v155, v0 offset:4
	ds_bpermute_b32 v167, v155, v0 offset:8
	ds_bpermute_b32 v168, v155, v0 offset:12
	ds_bpermute_b32 v169, v155, v0 offset:16
	ds_bpermute_b32 v170, v155, v0 offset:20
	ds_bpermute_b32 v171, v155, v0 offset:24
	ds_bpermute_b32 v172, v155, v0 offset:28
	ds_bpermute_b32 v173, v155, v1
	ds_bpermute_b32 v174, v155, v1 offset:4
	ds_bpermute_b32 v175, v155, v1 offset:8
	ds_bpermute_b32 v176, v155, v1 offset:12
	ds_bpermute_b32 v177, v155, v1 offset:16
	ds_bpermute_b32 v178, v155, v1 offset:20
	ds_bpermute_b32 v179, v155, v1 offset:24
	ds_bpermute_b32 v180, v155, v1 offset:28
	v_add_f32_e32 v3, v4, v3
	v_add_f32_e32 v3, v6, v3
	s_waitcnt lgkmcnt(0)
	v_cmp_eq_u32_e32 vcc, 1, v154
	s_nop 1
	v_cndmask_b32_e32 v9, v9, v156, vcc
	v_cndmask_b32_e32 v10, v10, v157, vcc
	v_cndmask_b32_e32 v11, v11, v158, vcc
	v_cndmask_b32_e32 v12, v12, v159, vcc
	v_cndmask_b32_e32 v13, v13, v160, vcc
	v_cndmask_b32_e32 v14, v14, v162, vcc
	v_cndmask_b32_e32 v15, v15, v163, vcc
	v_cndmask_b32_e32 v8, v8, v164, vcc
	v_cmp_eq_u32_e32 vcc, 2, v154
	s_nop 1
	v_cndmask_b32_e32 v9, v9, v165, vcc
	v_cndmask_b32_e32 v10, v10, v166, vcc
	v_cndmask_b32_e32 v11, v11, v167, vcc
	v_cndmask_b32_e32 v12, v12, v168, vcc
	v_cndmask_b32_e32 v13, v13, v169, vcc
	v_cndmask_b32_e32 v14, v14, v170, vcc
	v_cndmask_b32_e32 v15, v15, v171, vcc
	v_cndmask_b32_e32 v8, v8, v172, vcc
	v_cmp_eq_u32_e32 vcc, 3, v154
	s_nop 1
	v_cndmask_b32_e32 v9, v9, v173, vcc
	v_cndmask_b32_e32 v10, v10, v174, vcc
	v_cndmask_b32_e32 v11, v11, v175, vcc
	v_cndmask_b32_e32 v12, v12, v176, vcc
	v_cndmask_b32_e32 v13, v13, v177, vcc
	v_cndmask_b32_e32 v14, v14, v178, vcc
	v_cndmask_b32_e32 v15, v15, v179, vcc
	v_cndmask_b32_e32 v8, v8, v180, vcc
	s_waitcnt lgkmcnt(6)
	v_max_f32_e32 v4, v10, v10
	v_max_f32_e32 v6, v9, v9
	v_max_f32_e32 v4, v6, v4
	s_waitcnt lgkmcnt(4)
	v_max3_f32 v4, v4, v11, v12
	s_waitcnt lgkmcnt(2)
	v_max3_f32 v4, v4, v13, v14
	s_waitcnt lgkmcnt(0)
; DEVI void phase_p7(const int TIDX, const int BIDX, const int GDIM, KAP KA, unsigned char* WSB, float* OUTB, int l, unsigned char* smem) {
;     ...
;         float pe[8], es = 0.f;
; #pragma unroll
;         for (int j = 0; j < 8; ++j) { pe[j] = expf(el[j] - em); es += pe[j]; }
; #pragma unroll
;         for (int j = 0; j < 8; ++j) pe[j] = pe[j] / es;
	v_max3_f32 v4, v4, v15, v8
	v_sub_f32_e32 v6, v9, v4
	v_mul_f32_e32 v7, 0x3fb8aa3b, v6
	v_fma_f32 v9, v6, s61, -v7
	v_rndne_f32_e32 v16, v7
	v_fmac_f32_e32 v9, 0x32a5705f, v6
	v_sub_f32_e32 v7, v7, v16
	v_add_f32_e32 v7, v7, v9
	v_exp_f32_e32 v7, v7
	v_cvt_i32_f32_e32 v9, v16
	v_cmp_ngt_f32_e32 vcc, s90, v6
	v_mov_b32_e32 v2, 0
	v_ldexp_f32 v7, v7, v9
	v_cndmask_b32_e32 v7, 0, v7, vcc
	v_cmp_nlt_f32_e32 vcc, s91, v6
	s_nop 1
	v_cndmask_b32_e32 v6, v229, v7, vcc
	v_sub_f32_e32 v7, v10, v4
	v_mul_f32_e32 v9, 0x3fb8aa3b, v7
	v_fma_f32 v10, v7, s61, -v9
	v_rndne_f32_e32 v16, v9
	v_fmac_f32_e32 v10, 0x32a5705f, v7
	v_sub_f32_e32 v9, v9, v16
	v_add_f32_e32 v9, v9, v10
	v_exp_f32_e32 v9, v9
	v_cvt_i32_f32_e32 v10, v16
	v_cmp_ngt_f32_e32 vcc, s90, v7
	v_ldexp_f32 v9, v9, v10
	v_sub_f32_e32 v10, v11, v4
	v_mul_f32_e32 v11, 0x3fb8aa3b, v10
	v_fma_f32 v16, v10, s61, -v11
	v_rndne_f32_e32 v17, v11
	v_fmac_f32_e32 v16, 0x32a5705f, v10
	v_sub_f32_e32 v11, v11, v17
	v_add_f32_e32 v11, v11, v16
	v_exp_f32_e32 v11, v11
	v_cvt_i32_f32_e32 v16, v17
	v_cndmask_b32_e32 v9, 0, v9, vcc
	v_cmp_nlt_f32_e32 vcc, s91, v7
	v_ldexp_f32 v11, v11, v16
	s_nop 0
	v_cndmask_b32_e32 v7, v229, v9, vcc
	v_cmp_ngt_f32_e32 vcc, s90, v10
	v_add_f32_e32 v9, v6, v7
	s_nop 0
	v_cndmask_b32_e32 v11, 0, v11, vcc
	v_cmp_nlt_f32_e32 vcc, s91, v10
	s_nop 1
	v_cndmask_b32_e32 v10, v229, v11, vcc
	v_sub_f32_e32 v11, v12, v4
	v_mul_f32_e32 v12, 0x3fb8aa3b, v11
	v_fma_f32 v16, v11, s61, -v12
	v_rndne_f32_e32 v17, v12
	v_fmac_f32_e32 v16, 0x32a5705f, v11
	v_sub_f32_e32 v12, v12, v17
	v_add_f32_e32 v12, v12, v16
	v_exp_f32_e32 v12, v12
	v_cvt_i32_f32_e32 v16, v17
	v_cmp_ngt_f32_e32 vcc, s90, v11
	v_add_f32_e32 v9, v10, v9
	v_ldexp_f32 v12, v12, v16
	v_cndmask_b32_e32 v12, 0, v12, vcc
	v_cmp_nlt_f32_e32 vcc, s91, v11
	s_nop 1
	v_cndmask_b32_e32 v11, v229, v12, vcc
	v_sub_f32_e32 v12, v13, v4
	v_mul_f32_e32 v13, 0x3fb8aa3b, v12
	v_fma_f32 v16, v12, s61, -v13
	v_rndne_f32_e32 v17, v13
	v_fmac_f32_e32 v16, 0x32a5705f, v12
	v_sub_f32_e32 v13, v13, v17
	v_add_f32_e32 v13, v13, v16
	v_exp_f32_e32 v13, v13
	v_cvt_i32_f32_e32 v16, v17
	v_cmp_ngt_f32_e32 vcc, s90, v12
	v_add_f32_e32 v9, v11, v9
	v_ldexp_f32 v13, v13, v16
	v_cndmask_b32_e32 v13, 0, v13, vcc
	v_cmp_nlt_f32_e32 vcc, s91, v12
	s_nop 1
	v_cndmask_b32_e32 v12, v229, v13, vcc
	v_sub_f32_e32 v13, v14, v4
	v_mul_f32_e32 v14, 0x3fb8aa3b, v13
	v_fma_f32 v16, v13, s61, -v14
	v_rndne_f32_e32 v17, v14
	v_fmac_f32_e32 v16, 0x32a5705f, v13
	v_sub_f32_e32 v14, v14, v17
	v_add_f32_e32 v14, v14, v16
	v_exp_f32_e32 v14, v14
	v_cvt_i32_f32_e32 v16, v17
	v_cmp_ngt_f32_e32 vcc, s90, v13
	v_add_f32_e32 v9, v12, v9
	v_ldexp_f32 v14, v14, v16
	v_cndmask_b32_e32 v14, 0, v14, vcc
	v_cmp_nlt_f32_e32 vcc, s91, v13
	s_nop 1
	v_cndmask_b32_e32 v13, v229, v14, vcc
	v_sub_f32_e32 v14, v15, v4
	v_mul_f32_e32 v15, 0x3fb8aa3b, v14
	v_fma_f32 v16, v14, s61, -v15
	v_rndne_f32_e32 v17, v15
	v_fmac_f32_e32 v16, 0x32a5705f, v14
	v_sub_f32_e32 v15, v15, v17
	v_add_f32_e32 v15, v15, v16
	v_exp_f32_e32 v15, v15
	v_cvt_i32_f32_e32 v16, v17
	v_cmp_ngt_f32_e32 vcc, s90, v14
	v_sub_f32_e32 v4, v8, v4
	v_mul_f32_e32 v8, 0x3fb8aa3b, v4
	v_ldexp_f32 v15, v15, v16
	v_cndmask_b32_e32 v15, 0, v15, vcc
	v_cmp_nlt_f32_e32 vcc, s91, v14
	v_rndne_f32_e32 v16, v8
	v_add_f32_e32 v9, v13, v9
	v_cndmask_b32_e32 v14, v229, v15, vcc
	v_fma_f32 v15, v4, s61, -v8
	v_fmac_f32_e32 v15, 0x32a5705f, v4
	v_sub_f32_e32 v8, v8, v16
	v_add_f32_e32 v8, v8, v15
	v_exp_f32_e32 v8, v8
	v_cvt_i32_f32_e32 v15, v16
	v_cmp_ngt_f32_e32 vcc, s90, v4
	v_add_f32_e32 v9, v14, v9
	v_ldexp_f32 v8, v8, v15
	v_cndmask_b32_e32 v8, 0, v8, vcc
	v_cmp_nlt_f32_e32 vcc, s91, v4
	s_nop 1
	v_cndmask_b32_e32 v4, v229, v8, vcc
	v_add_f32_e32 v8, v4, v9
	v_div_scale_f32 v9, s[0:1], v8, v8, v6
	v_rcp_f32_e32 v15, v9
	s_nop 0
	v_fma_f32 v16, -v9, v15, 1.0
	v_fmac_f32_e32 v15, v16, v15
	v_div_scale_f32 v16, vcc, v6, v8, v6
	v_mul_f32_e32 v17, v16, v15
	v_fma_f32 v18, -v9, v17, v16
	v_fmac_f32_e32 v17, v18, v15
	v_fma_f32 v9, -v9, v17, v16
	v_div_fmas_f32 v9, v9, v15, v17
	v_div_fixup_f32 v6, v9, v8, v6
	v_div_scale_f32 v9, s[0:1], v8, v8, v7
	v_rcp_f32_e32 v15, v9
	v_cmp_nlt_f32_e64 s[24:25], -1.0, v6
	v_fma_f32 v16, -v9, v15, 1.0
	v_fmac_f32_e32 v15, v16, v15
	v_div_scale_f32 v16, vcc, v7, v8, v7
	v_mul_f32_e32 v17, v16, v15
	v_fma_f32 v18, -v9, v17, v16
	v_fmac_f32_e32 v17, v18, v15
	v_fma_f32 v9, -v9, v17, v16
	v_div_fmas_f32 v9, v9, v15, v17
	v_div_fixup_f32 v9, v9, v8, v7
	v_div_scale_f32 v7, s[0:1], v8, v8, v10
	v_rcp_f32_e32 v15, v7
	s_nop 0
	v_fma_f32 v16, -v7, v15, 1.0
	v_fmac_f32_e32 v15, v16, v15
	v_div_scale_f32 v16, vcc, v10, v8, v10
	v_mul_f32_e32 v17, v16, v15
	v_fma_f32 v18, -v7, v17, v16
	v_fmac_f32_e32 v17, v18, v15
	v_fma_f32 v7, -v7, v17, v16
; DEVI void phase_p7(const int TIDX, const int BIDX, const int GDIM, KAP KA, unsigned char* WSB, float* OUTB, int l, unsigned char* smem) {
;     ...
;         for (int j = 0; j < 8; ++j) pe[j] = pe[j] / es;
;         int i1 = 0; float p1 = pe[0];
; #pragma unroll
;         for (int j = 1; j < 8; ++j) if (pe[j] > p1) { p1 = pe[j]; i1 = j; }
;         int i2 = -1; float p2 = -1.f;
; #pragma unroll
;         for (int j = 0; j < 8; ++j) if (j != i1 && pe[j] > p2) { p2 = pe[j]; i2 = j; }
;         const float den = p1 + p2;
;         if (lane == 2 * t) { my_e = gi * 8 + i1; my_w = gtop * (p1 / den); my_tk = tok * 2; }
;         if (lane == 2 * t + 1) { my_e = gi * 8 + i2; my_w = gtop * (p2 / den); my_tk = tok * 2 + 1; }
;       }
;       if (lane < 8) {
;         const int sl = atomicAdd(cnt + my_e * 32, 1);
	v_div_fmas_f32 v7, v7, v15, v17
	v_div_fixup_f32 v10, v7, v8, v10
	v_div_scale_f32 v7, s[0:1], v8, v8, v11
	v_rcp_f32_e32 v15, v7
	s_nop 0
	v_fma_f32 v16, -v7, v15, 1.0
	v_fmac_f32_e32 v15, v16, v15
	v_div_scale_f32 v16, vcc, v11, v8, v11
	v_mul_f32_e32 v17, v16, v15
	v_fma_f32 v18, -v7, v17, v16
	v_fmac_f32_e32 v17, v18, v15
	v_fma_f32 v7, -v7, v17, v16
	v_div_fmas_f32 v7, v7, v15, v17
	v_div_fixup_f32 v11, v7, v8, v11
	v_div_scale_f32 v7, s[0:1], v8, v8, v12
	v_rcp_f32_e32 v15, v7
	s_nop 0
	v_fma_f32 v16, -v7, v15, 1.0
	v_fmac_f32_e32 v15, v16, v15
	v_div_scale_f32 v16, vcc, v12, v8, v12
	v_mul_f32_e32 v17, v16, v15
	v_fma_f32 v18, -v7, v17, v16
	v_fmac_f32_e32 v17, v18, v15
	v_fma_f32 v7, -v7, v17, v16
	v_div_fmas_f32 v7, v7, v15, v17
	v_div_fixup_f32 v12, v7, v8, v12
	v_div_scale_f32 v7, s[0:1], v8, v8, v13
	v_rcp_f32_e32 v15, v7
	s_nop 0
	v_fma_f32 v16, -v7, v15, 1.0
	v_fmac_f32_e32 v15, v16, v15
	v_div_scale_f32 v16, vcc, v13, v8, v13
	v_mul_f32_e32 v17, v16, v15
	v_fma_f32 v18, -v7, v17, v16
	v_fmac_f32_e32 v17, v18, v15
	v_fma_f32 v7, -v7, v17, v16
	v_div_fmas_f32 v7, v7, v15, v17
	v_div_fixup_f32 v13, v7, v8, v13
	v_div_scale_f32 v7, s[0:1], v8, v8, v14
	v_rcp_f32_e32 v15, v7
	s_nop 0
	v_fma_f32 v16, -v7, v15, 1.0
	v_fmac_f32_e32 v15, v16, v15
	v_div_scale_f32 v16, vcc, v14, v8, v14
	v_mul_f32_e32 v17, v16, v15
	v_fma_f32 v18, -v7, v17, v16
	v_fmac_f32_e32 v17, v18, v15
	v_fma_f32 v7, -v7, v17, v16
	v_div_fmas_f32 v7, v7, v15, v17
	v_div_fixup_f32 v14, v7, v8, v14
	v_div_scale_f32 v7, s[0:1], v8, v8, v4
	v_rcp_f32_e32 v15, v7
	s_nop 0
	v_fma_f32 v16, -v7, v15, 1.0
	v_fmac_f32_e32 v15, v16, v15
	v_div_scale_f32 v16, vcc, v4, v8, v4
	v_mul_f32_e32 v17, v16, v15
	v_fma_f32 v18, -v7, v17, v16
	v_fmac_f32_e32 v17, v18, v15
	v_fma_f32 v7, -v7, v17, v16
	v_div_fmas_f32 v7, v7, v15, v17
	v_cmp_gt_f32_e32 vcc, v9, v6
	v_div_fixup_f32 v4, v7, v8, v4
	s_nop 0
	v_cndmask_b32_e32 v8, v6, v9, vcc
	v_cndmask_b32_e64 v7, 0, 1, vcc
	v_cmp_gt_f32_e32 vcc, v10, v8
	s_nop 1
	v_cndmask_b32_e32 v8, v8, v10, vcc
	v_cndmask_b32_e64 v7, v7, 2, vcc
	v_cmp_gt_f32_e32 vcc, v11, v8
	s_nop 1
	v_cndmask_b32_e32 v8, v8, v11, vcc
	v_cndmask_b32_e64 v7, v7, 3, vcc
	v_cmp_gt_f32_e32 vcc, v12, v8
	s_nop 1
	v_cndmask_b32_e32 v8, v8, v12, vcc
	v_cndmask_b32_e64 v7, v7, 4, vcc
	v_cmp_gt_f32_e32 vcc, v13, v8
	s_nop 1
	v_cndmask_b32_e32 v8, v8, v13, vcc
	v_cndmask_b32_e64 v7, v7, 5, vcc
	v_cmp_gt_f32_e32 vcc, v14, v8
	s_nop 1
	v_cndmask_b32_e32 v15, v8, v14, vcc
	v_cndmask_b32_e64 v7, v7, 6, vcc
	v_cmp_ngt_f32_e64 s[36:37], v4, v15
	s_and_b64 s[2:3], vcc, s[36:37]
	s_nop 0
	v_cndmask_b32_e64 v8, 7, v7, s[36:37]
	v_cmp_eq_u32_e64 s[22:23], 0, v8
	s_or_b64 s[0:1], s[24:25], s[22:23]
	v_cndmask_b32_e64 v6, v6, -1.0, s[0:1]
	v_cmp_ne_u32_e64 s[22:23], 1, v8
	v_cmp_gt_f32_e64 s[24:25], v9, v6
	s_and_b64 s[22:23], s[22:23], s[24:25]
	v_cndmask_b32_e64 v6, v6, v9, s[22:23]
	v_cmp_ne_u32_e64 s[24:25], 2, v8
	v_cmp_gt_f32_e64 s[26:27], v10, v6
	s_and_b64 s[24:25], s[24:25], s[26:27]
	v_cndmask_b32_e64 v6, v6, v10, s[24:25]
	v_cmp_ne_u32_e64 s[26:27], 3, v8
	v_cmp_gt_f32_e64 s[28:29], v11, v6
	s_and_b64 s[26:27], s[26:27], s[28:29]
	v_cndmask_b32_e64 v6, v6, v11, s[26:27]
	v_cmp_ne_u32_e64 s[28:29], 4, v8
	v_cmp_gt_f32_e64 s[30:31], v12, v6
	s_and_b64 s[28:29], s[28:29], s[30:31]
	v_cndmask_b32_e64 v6, v6, v12, s[28:29]
	v_cmp_ne_u32_e64 s[30:31], 5, v8
	v_cmp_gt_f32_e64 s[34:35], v13, v6
	s_and_b64 s[34:35], s[30:31], s[34:35]
	v_cndmask_b32_e64 v7, v4, v15, s[36:37]
	v_cndmask_b32_e64 v6, v6, v13, s[34:35]
	v_cmp_ngt_f32_e32 vcc, v14, v6
	s_or_b64 s[30:31], s[2:3], vcc
	v_cndmask_b32_e64 v6, v14, v6, s[30:31]
	v_cmp_gt_f32_e32 vcc, v4, v6
	s_and_b64 s[36:37], s[36:37], vcc
	v_cndmask_b32_e64 v6, v6, v4, s[36:37]
	v_div_scale_f32 v4, s[2:3], v3, v3, 1.0
	v_rcp_f32_e32 v9, v4
	s_nop 0
	v_fma_f32 v10, -v4, v9, 1.0
	v_fmac_f32_e32 v9, v10, v9
	v_div_scale_f32 v10, vcc, 1.0, v3, 1.0
	v_mul_f32_e32 v11, v10, v9
	v_fma_f32 v12, -v4, v11, v10
	v_fmac_f32_e32 v11, v12, v9
	v_fma_f32 v4, -v4, v11, v10
	v_div_fmas_f32 v4, v4, v9, v11
	v_div_fixup_f32 v9, v4, v3, 1.0
	v_add_f32_e32 v10, v7, v6
	v_mov_b32_e32 v4, 0
	v_mov_b32_e32 v3, 0
	s_or_b64 s[62:63], s[6:7], s[10:11]
	s_or_b64 s[62:63], s[62:63], s[14:15]
	s_or_b64 s[62:63], s[62:63], s[18:19]
	s_and_saveexec_b64 s[2:3], s[62:63]
	s_cbranch_execz .LBB0_72
	v_div_scale_f32 v2, s[62:63], v10, v10, v7
	v_rcp_f32_e32 v4, v2
	v_add_u32_e32 v3, v8, v5
	v_fma_f32 v8, -v2, v4, 1.0
	v_fmac_f32_e32 v4, v8, v4
	v_div_scale_f32 v8, vcc, v7, v10, v7
	v_mul_f32_e32 v11, v8, v4
	v_fma_f32 v12, -v2, v11, v8
	v_fmac_f32_e32 v11, v12, v4
	v_fma_f32 v2, -v2, v11, v8
	v_div_fmas_f32 v2, v2, v4, v11
	v_div_fixup_f32 v2, v2, v10, v7
	v_mul_f32_e32 v4, v9, v2
	v_lshl_or_b32 v2, v32, 3, v45
